# v3 + write-through (sc1) stores for the MLP hidden activations in both up-GEMM epilogues
# speedup vs baseline: 1.0029x; 1.0029x over previous
;     __device__ __forceinline__ void operator()(const f32x4 (&acc)[2][2][4][2], const Unit& u, int wr, int wc, int fr, int fq) const {
;     ...
;             const int col0 = u.pn * BM + wc * 32 + 8 * fq;
;             f32x4 c1v[2][2], c2v[2][2];
;             if (F == 1) {
; #pragma unroll
;                 for (int bj = 0; bj < 2; ++bj)
; #pragma unroll
;                     for (int n = 0; n < 2; ++n) { c1v[bj][n] = *(const f32x4*)(c1 + col0 + bj * HALF + 4 * n); c2v[bj][n] = *(const f32x4*)(c2 + col0 + bj * HALF + 4 * n); } }
;             float mean8[2][4], rstd8[2][4];
; #pragma unroll
;             for (int ai = 0; ai < 2; ++ai)
; #pragma unroll
;                 for (int m = 0; m < 4; ++m) { mean8[ai][m] = 0.f; rstd8[ai][m] = 1.f; if (F == 1) row_stats(row0 + ai * HALF + m * 16, mean8[ai][m], rstd8[ai][m]); }
; #pragma unroll
;             for (int ai = 0; ai < 2; ++ai)
; #pragma unroll
;                 for (int m = 0; m < 4; ++m) { const int row = row0 + ai * HALF + m * 16; bf16_t* rowp = O + (size_t)row * ldc + col0;
;                     const float mean = mean8[ai][m], rstd = rstd8[ai][m];
; #pragma unroll
;                     for (int bj = 0; bj < 2; ++bj) { f32x4 v0 = acc[ai][bj][m][0], v1 = acc[ai][bj][m][1];
;                         if (F == 1) { v0 = (v0 - c1v[bj][0] * mean) * rstd + c2v[bj][0]; v1 = (v1 - c1v[bj][1] * mean) * rstd + c2v[bj][1]; }
.LBB0_580:
	v_lshl_or_b32 v136, s86, 8, v197
	v_lshl_add_u32 v186, s38, 8, v193
	v_ashrrev_i32_e32 v137, 31, v136
	v_lshlrev_b32_e32 v142, 1, v186
	v_lshlrev_b64 v[138:139], 2, v[136:137]
	v_ashrrev_i32_e32 v143, 31, v142
	v_lshl_add_u64 v[140:141], s[12:13], 0, v[138:139]
	v_lshl_add_u64 v[144:145], v[142:143], 2, s[10:11]
	flat_load_dwordx4 v[132:135], v[140:141]
	flat_load_dwordx4 v[128:131], v[140:141] offset:16
	flat_load_dwordx2 v[178:179], v[144:145]
	flat_load_dwordx2 v[180:181], v[144:145] offset:128
	flat_load_dwordx2 v[182:183], v[144:145] offset:256
	flat_load_dwordx2 v[184:185], v[144:145] offset:384
	v_add_u32_e32 v144, 0x100, v142
	v_ashrrev_i32_e32 v145, 31, v144
	v_add_u32_e32 v146, 0x120, v142
	v_add_u32_e32 v148, 0x140, v142
	v_add_u32_e32 v142, 0x160, v142
	v_lshl_add_u64 v[144:145], v[144:145], 2, s[10:11]
	v_ashrrev_i32_e32 v147, 31, v146
	v_ashrrev_i32_e32 v149, 31, v148
	v_ashrrev_i32_e32 v143, 31, v142
	v_lshl_add_u64 v[146:147], v[146:147], 2, s[10:11]
	v_lshl_add_u64 v[148:149], v[148:149], 2, s[10:11]
	v_lshl_add_u64 v[142:143], v[142:143], 2, s[10:11]
	flat_load_dwordx2 v[202:203], v[144:145]
	flat_load_dwordx2 v[208:209], v[146:147]
	flat_load_dwordx2 v[210:211], v[148:149]
	flat_load_dwordx2 v[212:213], v[142:143]
	v_lshl_add_u64 v[138:139], s[14:15], 0, v[138:139]
	flat_load_dwordx4 v[156:159], v[138:139]
	flat_load_dwordx4 v[152:155], v[138:139] offset:16
	v_ashrrev_i32_e32 v187, 31, v186
	flat_load_dwordx4 v[144:147], v[140:141] offset:512
	v_lshlrev_b64 v[142:143], 14, v[186:187]
	v_lshlrev_b64 v[190:191], 1, v[136:137]
	v_lshl_add_u64 v[176:177], s[8:9], 0, v[142:143]
	flat_load_dwordx4 v[140:143], v[140:141] offset:528
	s_nop 0
	flat_load_dwordx4 v[148:151], v[138:139] offset:512
	s_nop 0
	flat_load_dwordx4 v[136:139], v[138:139] offset:528
	v_lshl_add_u64 v[176:177], v[176:177], 0, v[190:191]
	s_mov_b32 s29, 0x200000
	s_mov_b64 s[40:41], 0x200000
	s_waitcnt vmcnt(0) lgkmcnt(0)
	v_pk_mul_f32 v[214:215], v[178:179], s[20:21] op_sel_hi:[1,0]
	s_nop 0
	v_fma_f32 v187, -v214, v214, v215
	v_pk_mul_f32 v[216:217], v[180:181], s[20:21] op_sel_hi:[1,0]
	v_pk_mul_f32 v[188:189], v[184:185], s[20:21] op_sel_hi:[1,0]
	v_xor_b32_e32 v179, 0x80000000, v131
	v_xor_b32_e32 v178, 0x80000000, v130
	v_fma_f32 v218, -v188, v188, v189
	v_pk_mul_f32 v[194:195], v[182:183], s[20:21] op_sel_hi:[1,0]
	v_fma_f32 v192, -v216, v216, v217
	v_xor_b32_e32 v135, 0x80000000, v135
	v_xor_b32_e32 v134, 0x80000000, v134
	v_fma_f32 v201, -v194, v194, v195
	v_pk_fma_f32 v[104:105], v[128:129], v[216:217], v[104:105] op_sel_hi:[1,0,1] neg_lo:[1,0,0] neg_hi:[1,0,0]
	v_pk_mul_f32 v[184:185], v[202:203], s[20:21] op_sel_hi:[1,0]
	v_pk_mul_f32 v[182:183], v[208:209], s[20:21] op_sel_hi:[1,0]
	v_pk_mul_f32 v[180:181], v[210:211], s[20:21] op_sel_hi:[1,0]
	v_pk_fma_f32 v[210:211], v[128:129], v[214:215], v[120:121] op_sel_hi:[1,0,1] neg_lo:[1,0,0] neg_hi:[1,0,0]
	v_max_f32_e32 v120, 0, v187
	v_add_f32_e32 v120, 0x3727c5ac, v120
	v_pk_mul_f32 v[130:131], v[212:213], s[20:21] op_sel_hi:[1,0]
	v_pk_fma_f32 v[212:213], v[178:179], v[214:215], v[122:123] op_sel_hi:[1,0,1]
	v_max_f32_e32 v123, 0, v218
	v_rsq_f32_e32 v218, v120
	v_pk_fma_f32 v[202:203], v[132:133], v[214:215], v[124:125] op_sel_hi:[1,0,1] neg_lo:[1,0,0] neg_hi:[1,0,0]
	v_max_f32_e32 v121, 0, v192
	v_fma_f32 v125, -v182, v182, v183
	v_pk_fma_f32 v[208:209], v[134:135], v[214:215], v[126:127] op_sel_hi:[1,0,1]
	v_fma_f32 v124, -v184, v184, v185
	v_add_f32_e32 v121, 0x3727c5ac, v121
	v_max_f32_e32 v125, 0, v125
	v_max_f32_e32 v124, 0, v124
	v_rsq_f32_e32 v220, v121
	v_add_f32_e32 v121, 0x3727c5ac, v125
	v_pk_fma_f32 v[208:209], v[208:209], v[218:219], v[158:159] op_sel_hi:[1,0,1]
	v_pk_fma_f32 v[202:203], v[202:203], v[218:219], v[156:157] op_sel_hi:[1,0,1]
	v_pk_fma_f32 v[212:213], v[212:213], v[218:219], v[154:155] op_sel_hi:[1,0,1]
	v_max_f32_e32 v122, 0, v201
	v_fma_f32 v127, -v130, v130, v131
	v_add_f32_e32 v120, 0x3727c5ac, v124
	v_rsq_f32_e32 v124, v121
	v_max_f32_e32 v121, 0, v202
	v_max_f32_e32 v125, 0, v203
	v_max_f32_e32 v187, 0, v208
	v_max_f32_e32 v201, 0, v212
	v_max_f32_e32 v202, 0, v209
	v_max_f32_e32 v203, 0, v213
	v_add_f32_e32 v123, 0x3727c5ac, v123
	v_max_f32_e32 v127, 0, v127
	v_pk_fma_f32 v[210:211], v[210:211], v[218:219], v[152:153] op_sel_hi:[1,0,1]
	v_mul_f32_e32 v187, v187, v187
	v_mul_f32_e32 v201, v201, v201
	v_mul_f32_e32 v202, v202, v202
	v_mul_f32_e32 v203, v203, v203
	v_rsq_f32_e32 v192, v123
	v_add_f32_e32 v123, 0x3727c5ac, v127
	v_max_f32_e32 v127, 0, v211
	v_cvt_pk_f16_f32 v209, v187, v202
	v_cvt_pk_f16_f32 v211, v201, v203
	v_pk_fma_f32 v[202:203], v[144:145], v[214:215], v[116:117] op_sel_hi:[1,0,1] neg_lo:[1,0,0] neg_hi:[1,0,0]
	v_fma_f32 v126, -v180, v180, v181
	v_xor_b32_e32 v117, 0x80000000, v147
	v_xor_b32_e32 v116, 0x80000000, v146
	v_pk_fma_f32 v[146:147], v[202:203], v[218:219], v[148:149] op_sel_hi:[1,0,1]
	v_pk_fma_f32 v[202:203], v[140:141], v[214:215], v[112:113] op_sel_hi:[1,0,1] neg_lo:[1,0,0] neg_hi:[1,0,0]
	v_xor_b32_e32 v113, 0x80000000, v143
	v_xor_b32_e32 v112, 0x80000000, v142
	v_add_f32_e32 v122, 0x3727c5ac, v122
	v_max_f32_e32 v126, 0, v126
	v_pk_fma_f32 v[114:115], v[112:113], v[214:215], v[114:115] op_sel_hi:[1,0,1]
	v_rsq_f32_e32 v222, v122
	v_add_f32_e32 v122, 0x3727c5ac, v126
	v_rsq_f32_e32 v126, v120
	v_rsq_f32_e32 v120, v123
	v_max_f32_e32 v123, 0, v210
	v_pk_fma_f32 v[114:115], v[114:115], v[218:219], v[138:139] op_sel_hi:[1,0,1]
	v_mul_f32_e32 v121, v121, v121
	v_mul_f32_e32 v123, v123, v123
	v_mul_f32_e32 v125, v125, v125
	v_mul_f32_e32 v127, v127, v127
	v_pk_fma_f32 v[118:119], v[116:117], v[214:215], v[118:119] op_sel_hi:[1,0,1]
;     __device__ __forceinline__ void operator()(const f32x4 (&acc)[2][2][4][2], const Unit& u, int wr, int wc, int fr, int fq) const {
;     ...
;                 for (int m = 0; m < 4; ++m) { const int row = row0 + ai * HALF + m * 16; bf16_t* rowp = O + (size_t)row * ldc + col0;
;                     const float mean = mean8[ai][m], rstd = rstd8[ai][m];
; #pragma unroll
;                     for (int bj = 0; bj < 2; ++bj) { f32x4 v0 = acc[ai][bj][m][0], v1 = acc[ai][bj][m][1];
;                         if (F == 1) { v0 = (v0 - c1v[bj][0] * mean) * rstd + c2v[bj][0]; v1 = (v1 - c1v[bj][1] * mean) * rstd + c2v[bj][1]; }
;                         if (kind == 1) {
; #pragma unroll
;                             for (int e = 0; e < 4; ++e) { float a = fmaxf(v0[e], 0.f), b_ = fmaxf(v1[e], 0.f); v0[e] = a * a; v1[e] = b_ * b_; } }
;                         u32x4 w; w.x = pk16(v0[0], v0[1]); w.y = pk16(v0[2], v0[3]); w.z = pk16(v1[0], v1[1]); w.w = pk16(v1[2], v1[3]);
;                         *(u32x4*)(rowp + bj * HALF) = w; } }
	v_max_f32_e32 v114, 0, v114
	v_max_f32_e32 v115, 0, v115
	v_cvt_pk_f16_f32 v208, v121, v125
	v_cvt_pk_f16_f32 v210, v123, v127
	v_pk_fma_f32 v[118:119], v[118:119], v[218:219], v[150:151] op_sel_hi:[1,0,1]
	v_mul_f32_e32 v114, v114, v114
	v_mul_f32_e32 v115, v115, v115
	v_pk_fma_f32 v[106:107], v[178:179], v[216:217], v[106:107] op_sel_hi:[1,0,1]
	flat_store_dwordx4 v[176:177], v[208:211] sc1
	v_max_f32_e32 v118, 0, v118
	v_max_f32_e32 v119, 0, v119
	v_cvt_pk_f16_f32 v211, v114, v115
	v_or_b32_e32 v114, 16, v186
	v_pk_fma_f32 v[108:109], v[132:133], v[216:217], v[108:109] op_sel_hi:[1,0,1] neg_lo:[1,0,0] neg_hi:[1,0,0]
	v_pk_fma_f32 v[110:111], v[134:135], v[216:217], v[110:111] op_sel_hi:[1,0,1]
	v_pk_fma_f32 v[106:107], v[106:107], v[220:221], v[154:155] op_sel_hi:[1,0,1]
	v_pk_fma_f32 v[104:105], v[104:105], v[220:221], v[152:153] op_sel_hi:[1,0,1]
	v_mul_f32_e32 v118, v118, v118
	v_mul_f32_e32 v119, v119, v119
	v_ashrrev_i32_e32 v115, 31, v114
	v_pk_fma_f32 v[110:111], v[110:111], v[220:221], v[158:159] op_sel_hi:[1,0,1]
	v_pk_fma_f32 v[108:109], v[108:109], v[220:221], v[156:157] op_sel_hi:[1,0,1]
	v_max_f32_e32 v104, 0, v104
	v_max_f32_e32 v105, 0, v105
	v_max_f32_e32 v106, 0, v106
	v_cvt_pk_f16_f32 v209, v118, v119
	v_lshlrev_b64 v[114:115], 14, v[114:115]
	v_max_f32_e32 v108, 0, v108
	v_mul_f32_e32 v118, v104, v104
	v_max_f32_e32 v104, 0, v109
	v_mul_f32_e32 v109, v105, v105
	v_max_f32_e32 v105, 0, v110
	v_mul_f32_e32 v110, v106, v106
	v_max_f32_e32 v106, 0, v111
	v_max_f32_e32 v107, 0, v107
	v_pk_fma_f32 v[96:97], v[140:141], v[216:217], v[96:97] op_sel_hi:[1,0,1] neg_lo:[1,0,0] neg_hi:[1,0,0]
	v_pk_fma_f32 v[98:99], v[112:113], v[216:217], v[98:99] op_sel_hi:[1,0,1]
	v_lshl_add_u64 v[114:115], s[8:9], 0, v[114:115]
	v_mul_f32_e32 v108, v108, v108
	v_mul_f32_e32 v104, v104, v104
	v_mul_f32_e32 v105, v105, v105
	v_mul_f32_e32 v106, v106, v106
	v_mul_f32_e32 v107, v107, v107
	v_pk_fma_f32 v[100:101], v[144:145], v[216:217], v[100:101] op_sel_hi:[1,0,1] neg_lo:[1,0,0] neg_hi:[1,0,0]
	v_pk_fma_f32 v[102:103], v[116:117], v[216:217], v[102:103] op_sel_hi:[1,0,1]
	v_pk_fma_f32 v[98:99], v[98:99], v[220:221], v[138:139] op_sel_hi:[1,0,1]
	v_pk_fma_f32 v[96:97], v[96:97], v[220:221], v[136:137] op_sel_hi:[1,0,1]
	v_lshl_add_u64 v[114:115], v[114:115], 0, v[190:191]
	v_cvt_pk_f16_f32 v104, v108, v104
	v_cvt_pk_f16_f32 v105, v105, v106
	v_cvt_pk_f16_f32 v106, v118, v109
	v_cvt_pk_f16_f32 v107, v110, v107
	v_pk_fma_f32 v[102:103], v[102:103], v[220:221], v[150:151] op_sel_hi:[1,0,1]
	v_pk_fma_f32 v[100:101], v[100:101], v[220:221], v[148:149] op_sel_hi:[1,0,1]
	v_max_f32_e32 v96, 0, v96
	v_max_f32_e32 v97, 0, v97
	v_max_f32_e32 v98, 0, v98
	flat_store_dwordx4 v[114:115], v[104:107] sc1
	v_max_f32_e32 v100, 0, v100
	v_max_f32_e32 v99, 0, v99
	v_mul_f32_e32 v104, v96, v96
	v_max_f32_e32 v96, 0, v101
	v_mul_f32_e32 v101, v97, v97
	v_max_f32_e32 v97, 0, v102
	v_mul_f32_e32 v102, v98, v98
	v_max_f32_e32 v98, 0, v103
	v_mul_f32_e32 v100, v100, v100
	v_mul_f32_e32 v96, v96, v96
	v_mul_f32_e32 v97, v97, v97
	v_mul_f32_e32 v98, v98, v98
	v_mul_f32_e32 v99, v99, v99
	v_cvt_pk_f16_f32 v96, v100, v96
	v_cvt_pk_f16_f32 v97, v97, v98
	v_cvt_pk_f16_f32 v98, v104, v101
	v_cvt_pk_f16_f32 v99, v102, v99
	v_pk_fma_f32 v[88:89], v[128:129], v[194:195], v[88:89] op_sel_hi:[1,0,1] neg_lo:[1,0,0] neg_hi:[1,0,0]
	v_pk_fma_f32 v[90:91], v[178:179], v[194:195], v[90:91] op_sel_hi:[1,0,1]
	flat_store_dwordx4 v[114:115], v[96:99] offset:256 sc1
	v_pk_fma_f32 v[92:93], v[132:133], v[194:195], v[92:93] op_sel_hi:[1,0,1] neg_lo:[1,0,0] neg_hi:[1,0,0]
	v_pk_fma_f32 v[94:95], v[134:135], v[194:195], v[94:95] op_sel_hi:[1,0,1]
	v_or_b32_e32 v96, 32, v186
	v_pk_fma_f32 v[90:91], v[90:91], v[222:223], v[154:155] op_sel_hi:[1,0,1]
	v_pk_fma_f32 v[88:89], v[88:89], v[222:223], v[152:153] op_sel_hi:[1,0,1]
	v_ashrrev_i32_e32 v97, 31, v96
	v_pk_fma_f32 v[94:95], v[94:95], v[222:223], v[158:159] op_sel_hi:[1,0,1]
	v_pk_fma_f32 v[92:93], v[92:93], v[222:223], v[156:157] op_sel_hi:[1,0,1]
	v_max_f32_e32 v88, 0, v88
	v_max_f32_e32 v89, 0, v89
	v_max_f32_e32 v90, 0, v90
	v_lshlrev_b64 v[96:97], 14, v[96:97]
	v_max_f32_e32 v92, 0, v92
	v_mul_f32_e32 v98, v88, v88
	v_max_f32_e32 v88, 0, v93
	v_mul_f32_e32 v93, v89, v89
	v_max_f32_e32 v89, 0, v94
	v_mul_f32_e32 v94, v90, v90
	v_max_f32_e32 v90, 0, v95
	v_max_f32_e32 v91, 0, v91
	v_pk_fma_f32 v[80:81], v[140:141], v[194:195], v[80:81] op_sel_hi:[1,0,1] neg_lo:[1,0,0] neg_hi:[1,0,0]
	v_pk_fma_f32 v[82:83], v[112:113], v[194:195], v[82:83] op_sel_hi:[1,0,1]
	v_lshl_add_u64 v[96:97], s[8:9], 0, v[96:97]
	v_mul_f32_e32 v92, v92, v92
	v_mul_f32_e32 v88, v88, v88
	v_mul_f32_e32 v89, v89, v89
	v_mul_f32_e32 v90, v90, v90
	v_mul_f32_e32 v91, v91, v91
	v_pk_fma_f32 v[84:85], v[144:145], v[194:195], v[84:85] op_sel_hi:[1,0,1] neg_lo:[1,0,0] neg_hi:[1,0,0]
	v_pk_fma_f32 v[86:87], v[116:117], v[194:195], v[86:87] op_sel_hi:[1,0,1]
	v_pk_fma_f32 v[82:83], v[82:83], v[222:223], v[138:139] op_sel_hi:[1,0,1]
	v_pk_fma_f32 v[80:81], v[80:81], v[222:223], v[136:137] op_sel_hi:[1,0,1]
	v_lshl_add_u64 v[96:97], v[96:97], 0, v[190:191]
	v_cvt_pk_f16_f32 v88, v92, v88
	v_cvt_pk_f16_f32 v89, v89, v90
	v_cvt_pk_f16_f32 v90, v98, v93
	v_cvt_pk_f16_f32 v91, v94, v91
	v_pk_fma_f32 v[86:87], v[86:87], v[222:223], v[150:151] op_sel_hi:[1,0,1]
	v_pk_fma_f32 v[84:85], v[84:85], v[222:223], v[148:149] op_sel_hi:[1,0,1]
	v_max_f32_e32 v80, 0, v80
	v_max_f32_e32 v81, 0, v81
	v_max_f32_e32 v82, 0, v82
	flat_store_dwordx4 v[96:97], v[88:91] sc1
	v_max_f32_e32 v84, 0, v84
	v_max_f32_e32 v83, 0, v83
	v_mul_f32_e32 v88, v80, v80
	v_max_f32_e32 v80, 0, v85
	v_mul_f32_e32 v85, v81, v81
;     __device__ __forceinline__ void operator()(const f32x4 (&acc)[2][2][4][2], const Unit& u, int wr, int wc, int fr, int fq) const {
;     ...
;                 for (int m = 0; m < 4; ++m) { const int row = row0 + ai * HALF + m * 16; bf16_t* rowp = O + (size_t)row * ldc + col0;
;                     const float mean = mean8[ai][m], rstd = rstd8[ai][m];
; #pragma unroll
;                     for (int bj = 0; bj < 2; ++bj) { f32x4 v0 = acc[ai][bj][m][0], v1 = acc[ai][bj][m][1];
;                         if (F == 1) { v0 = (v0 - c1v[bj][0] * mean) * rstd + c2v[bj][0]; v1 = (v1 - c1v[bj][1] * mean) * rstd + c2v[bj][1]; }
;                         if (kind == 1) {
; #pragma unroll
;                             for (int e = 0; e < 4; ++e) { float a = fmaxf(v0[e], 0.f), b_ = fmaxf(v1[e], 0.f); v0[e] = a * a; v1[e] = b_ * b_; } }
;                         u32x4 w; w.x = pk16(v0[0], v0[1]); w.y = pk16(v0[2], v0[3]); w.z = pk16(v1[0], v1[1]); w.w = pk16(v1[2], v1[3]);
;                         *(u32x4*)(rowp + bj * HALF) = w; } }
	v_max_f32_e32 v81, 0, v86
	v_mul_f32_e32 v86, v82, v82
	v_max_f32_e32 v82, 0, v87
	v_mul_f32_e32 v84, v84, v84
	v_mul_f32_e32 v80, v80, v80
	v_mul_f32_e32 v81, v81, v81
	v_mul_f32_e32 v82, v82, v82
	v_mul_f32_e32 v83, v83, v83
	v_cvt_pk_f16_f32 v80, v84, v80
	v_cvt_pk_f16_f32 v81, v81, v82
	v_cvt_pk_f16_f32 v82, v88, v85
	v_cvt_pk_f16_f32 v83, v86, v83
	v_pk_fma_f32 v[72:73], v[128:129], v[188:189], v[72:73] op_sel_hi:[1,0,1] neg_lo:[1,0,0] neg_hi:[1,0,0]
	v_pk_fma_f32 v[74:75], v[178:179], v[188:189], v[74:75] op_sel_hi:[1,0,1]
	flat_store_dwordx4 v[96:97], v[80:83] offset:256 sc1
	v_pk_fma_f32 v[76:77], v[132:133], v[188:189], v[76:77] op_sel_hi:[1,0,1] neg_lo:[1,0,0] neg_hi:[1,0,0]
	v_pk_fma_f32 v[78:79], v[134:135], v[188:189], v[78:79] op_sel_hi:[1,0,1]
	v_or_b32_e32 v80, 48, v186
	v_pk_fma_f32 v[74:75], v[74:75], v[192:193], v[154:155] op_sel_hi:[1,0,1]
	v_pk_fma_f32 v[72:73], v[72:73], v[192:193], v[152:153] op_sel_hi:[1,0,1]
	v_ashrrev_i32_e32 v81, 31, v80
	v_pk_fma_f32 v[78:79], v[78:79], v[192:193], v[158:159] op_sel_hi:[1,0,1]
	v_pk_fma_f32 v[76:77], v[76:77], v[192:193], v[156:157] op_sel_hi:[1,0,1]
	v_max_f32_e32 v72, 0, v72
	v_max_f32_e32 v73, 0, v73
	v_max_f32_e32 v74, 0, v74
	v_lshlrev_b64 v[80:81], 14, v[80:81]
	v_max_f32_e32 v76, 0, v76
	v_mul_f32_e32 v82, v72, v72
	v_max_f32_e32 v72, 0, v77
	v_mul_f32_e32 v77, v73, v73
	v_max_f32_e32 v73, 0, v78
	v_mul_f32_e32 v78, v74, v74
	v_max_f32_e32 v74, 0, v79
	v_max_f32_e32 v75, 0, v75
	v_pk_fma_f32 v[64:65], v[140:141], v[188:189], v[64:65] op_sel_hi:[1,0,1] neg_lo:[1,0,0] neg_hi:[1,0,0]
	v_pk_fma_f32 v[66:67], v[112:113], v[188:189], v[66:67] op_sel_hi:[1,0,1]
	v_pk_fma_f32 v[142:143], v[202:203], v[218:219], v[136:137] op_sel_hi:[1,0,1]
	v_lshl_add_u64 v[80:81], s[8:9], 0, v[80:81]
	v_mul_f32_e32 v76, v76, v76
	v_mul_f32_e32 v72, v72, v72
	v_mul_f32_e32 v73, v73, v73
	v_mul_f32_e32 v74, v74, v74
	v_mul_f32_e32 v75, v75, v75
	v_pk_fma_f32 v[68:69], v[144:145], v[188:189], v[68:69] op_sel_hi:[1,0,1] neg_lo:[1,0,0] neg_hi:[1,0,0]
	v_pk_fma_f32 v[70:71], v[116:117], v[188:189], v[70:71] op_sel_hi:[1,0,1]
	v_pk_fma_f32 v[66:67], v[66:67], v[192:193], v[138:139] op_sel_hi:[1,0,1]
	v_pk_fma_f32 v[64:65], v[64:65], v[192:193], v[136:137] op_sel_hi:[1,0,1]
	v_max_f32_e32 v127, 0, v143
	v_lshl_add_u64 v[80:81], v[80:81], 0, v[190:191]
	v_cvt_pk_f16_f32 v72, v76, v72
	v_cvt_pk_f16_f32 v73, v73, v74
	v_cvt_pk_f16_f32 v74, v82, v77
	v_cvt_pk_f16_f32 v75, v78, v75
	v_pk_fma_f32 v[70:71], v[70:71], v[192:193], v[150:151] op_sel_hi:[1,0,1]
	v_pk_fma_f32 v[68:69], v[68:69], v[192:193], v[148:149] op_sel_hi:[1,0,1]
	v_max_f32_e32 v64, 0, v64
	v_max_f32_e32 v65, 0, v65
	v_max_f32_e32 v66, 0, v66
	v_mul_f32_e32 v127, v127, v127
	flat_store_dwordx4 v[80:81], v[72:75] sc1
	v_max_f32_e32 v68, 0, v68
	v_max_f32_e32 v67, 0, v67
	v_mul_f32_e32 v72, v64, v64
	v_max_f32_e32 v64, 0, v69
	v_mul_f32_e32 v69, v65, v65
	v_max_f32_e32 v65, 0, v70
	v_mul_f32_e32 v70, v66, v66
	v_max_f32_e32 v66, 0, v71
	v_pk_fma_f32 v[56:57], v[128:129], v[184:185], v[56:57] op_sel_hi:[1,0,1] neg_lo:[1,0,0] neg_hi:[1,0,0]
	v_mul_f32_e32 v68, v68, v68
	v_mul_f32_e32 v64, v64, v64
	v_mul_f32_e32 v65, v65, v65
	v_mul_f32_e32 v66, v66, v66
	v_mul_f32_e32 v67, v67, v67
	v_pk_fma_f32 v[60:61], v[132:133], v[184:185], v[60:61] op_sel_hi:[1,0,1] neg_lo:[1,0,0] neg_hi:[1,0,0]
	v_pk_fma_f32 v[58:59], v[178:179], v[184:185], v[58:59] op_sel_hi:[1,0,1]
	v_pk_fma_f32 v[56:57], v[56:57], v[126:127], v[152:153] op_sel_hi:[1,0,1]
	v_cvt_pk_f16_f32 v64, v68, v64
	v_cvt_pk_f16_f32 v65, v65, v66
	v_cvt_pk_f16_f32 v66, v72, v69
	v_cvt_pk_f16_f32 v67, v70, v67
	v_pk_fma_f32 v[62:63], v[134:135], v[184:185], v[62:63] op_sel_hi:[1,0,1]
	v_pk_fma_f32 v[60:61], v[60:61], v[126:127], v[156:157] op_sel_hi:[1,0,1]
	v_pk_fma_f32 v[58:59], v[58:59], v[126:127], v[154:155] op_sel_hi:[1,0,1]
	v_max_f32_e32 v56, 0, v56
	flat_store_dwordx4 v[80:81], v[64:67] offset:256 sc1
	v_pk_fma_f32 v[62:63], v[62:63], v[126:127], v[158:159] op_sel_hi:[1,0,1]
	v_max_f32_e32 v60, 0, v60
	v_mul_f32_e32 v66, v56, v56
	v_max_f32_e32 v56, 0, v61
	v_max_f32_e32 v57, 0, v57
	v_max_f32_e32 v58, 0, v58
	v_mul_f32_e32 v60, v60, v60
	v_mul_f32_e32 v56, v56, v56
	v_mul_f32_e32 v61, v57, v57
	v_max_f32_e32 v57, 0, v62
	v_mul_f32_e32 v62, v58, v58
	v_max_f32_e32 v58, 0, v63
	v_max_f32_e32 v59, 0, v59
	v_pk_fma_f32 v[48:49], v[140:141], v[184:185], v[48:49] op_sel_hi:[1,0,1] neg_lo:[1,0,0] neg_hi:[1,0,0]
	v_pk_fma_f32 v[50:51], v[112:113], v[184:185], v[50:51] op_sel_hi:[1,0,1]
	v_mul_f32_e32 v57, v57, v57
	v_mul_f32_e32 v58, v58, v58
	v_mul_f32_e32 v59, v59, v59
	v_cvt_pk_f16_f32 v56, v60, v56
	v_add_co_u32_e32 v60, vcc, s29, v176
	v_pk_fma_f32 v[52:53], v[144:145], v[184:185], v[52:53] op_sel_hi:[1,0,1] neg_lo:[1,0,0] neg_hi:[1,0,0]
	v_pk_fma_f32 v[54:55], v[116:117], v[184:185], v[54:55] op_sel_hi:[1,0,1]
	v_pk_fma_f32 v[50:51], v[50:51], v[126:127], v[138:139] op_sel_hi:[1,0,1]
	v_pk_fma_f32 v[48:49], v[48:49], v[126:127], v[136:137] op_sel_hi:[1,0,1]
	v_max_f32_e32 v125, 0, v147
	v_cvt_pk_f16_f32 v57, v57, v58
	v_cvt_pk_f16_f32 v58, v66, v61
	v_cvt_pk_f16_f32 v59, v62, v59
	v_addc_co_u32_e32 v61, vcc, 0, v177, vcc
	v_pk_fma_f32 v[54:55], v[54:55], v[126:127], v[150:151] op_sel_hi:[1,0,1]
	v_pk_fma_f32 v[52:53], v[52:53], v[126:127], v[148:149] op_sel_hi:[1,0,1]
	v_max_f32_e32 v48, 0, v48
	v_max_f32_e32 v49, 0, v49
	v_max_f32_e32 v50, 0, v50
	v_mul_f32_e32 v125, v125, v125
	flat_store_dwordx4 v[60:61], v[56:59] sc1
	v_max_f32_e32 v52, 0, v52
	v_max_f32_e32 v51, 0, v51
	v_mul_f32_e32 v56, v48, v48
	v_max_f32_e32 v48, 0, v53
	v_mul_f32_e32 v53, v49, v49
	v_max_f32_e32 v49, 0, v54
;     __device__ __forceinline__ void operator()(const f32x4 (&acc)[2][2][4][2], const Unit& u, int wr, int wc, int fr, int fq) const {
;     ...
;                 for (int m = 0; m < 4; ++m) { const int row = row0 + ai * HALF + m * 16; bf16_t* rowp = O + (size_t)row * ldc + col0;
;                     const float mean = mean8[ai][m], rstd = rstd8[ai][m];
; #pragma unroll
;                     for (int bj = 0; bj < 2; ++bj) { f32x4 v0 = acc[ai][bj][m][0], v1 = acc[ai][bj][m][1];
;                         if (F == 1) { v0 = (v0 - c1v[bj][0] * mean) * rstd + c2v[bj][0]; v1 = (v1 - c1v[bj][1] * mean) * rstd + c2v[bj][1]; }
;                         if (kind == 1) {
; #pragma unroll
;                             for (int e = 0; e < 4; ++e) { float a = fmaxf(v0[e], 0.f), b_ = fmaxf(v1[e], 0.f); v0[e] = a * a; v1[e] = b_ * b_; } }
;                         u32x4 w; w.x = pk16(v0[0], v0[1]); w.y = pk16(v0[2], v0[3]); w.z = pk16(v1[0], v1[1]); w.w = pk16(v1[2], v1[3]);
;                         *(u32x4*)(rowp + bj * HALF) = w; } }
	v_mul_f32_e32 v54, v50, v50
	v_max_f32_e32 v50, 0, v55
	v_pk_fma_f32 v[40:41], v[128:129], v[182:183], v[40:41] op_sel_hi:[1,0,1] neg_lo:[1,0,0] neg_hi:[1,0,0]
	v_mul_f32_e32 v52, v52, v52
	v_mul_f32_e32 v48, v48, v48
	v_mul_f32_e32 v49, v49, v49
	v_mul_f32_e32 v50, v50, v50
	v_mul_f32_e32 v51, v51, v51
	v_pk_fma_f32 v[44:45], v[132:133], v[182:183], v[44:45] op_sel_hi:[1,0,1] neg_lo:[1,0,0] neg_hi:[1,0,0]
	v_pk_fma_f32 v[42:43], v[178:179], v[182:183], v[42:43] op_sel_hi:[1,0,1]
	v_pk_fma_f32 v[40:41], v[40:41], v[124:125], v[152:153] op_sel_hi:[1,0,1]
	v_lshl_add_u64 v[64:65], v[176:177], 0, s[40:41]
	v_cvt_pk_f16_f32 v48, v52, v48
	v_cvt_pk_f16_f32 v49, v49, v50
	v_cvt_pk_f16_f32 v50, v56, v53
	v_cvt_pk_f16_f32 v51, v54, v51
	v_pk_fma_f32 v[46:47], v[134:135], v[182:183], v[46:47] op_sel_hi:[1,0,1]
	v_pk_fma_f32 v[44:45], v[44:45], v[124:125], v[156:157] op_sel_hi:[1,0,1]
	v_pk_fma_f32 v[42:43], v[42:43], v[124:125], v[154:155] op_sel_hi:[1,0,1]
	v_max_f32_e32 v40, 0, v40
	flat_store_dwordx4 v[64:65], v[48:51] offset:256 sc1
	v_pk_fma_f32 v[46:47], v[46:47], v[124:125], v[158:159] op_sel_hi:[1,0,1]
	v_max_f32_e32 v44, 0, v44
	v_mul_f32_e32 v50, v40, v40
	v_max_f32_e32 v40, 0, v45
	v_max_f32_e32 v41, 0, v41
	v_max_f32_e32 v42, 0, v42
	v_rsq_f32_e32 v122, v122
	v_mul_f32_e32 v44, v44, v44
	v_mul_f32_e32 v40, v40, v40
	v_mul_f32_e32 v45, v41, v41
	v_max_f32_e32 v41, 0, v46
	v_mul_f32_e32 v46, v42, v42
	v_max_f32_e32 v42, 0, v47
	v_max_f32_e32 v43, 0, v43
	v_pk_fma_f32 v[32:33], v[140:141], v[182:183], v[32:33] op_sel_hi:[1,0,1] neg_lo:[1,0,0] neg_hi:[1,0,0]
	v_pk_fma_f32 v[34:35], v[112:113], v[182:183], v[34:35] op_sel_hi:[1,0,1]
	v_mul_f32_e32 v41, v41, v41
	v_mul_f32_e32 v42, v42, v42
	v_mul_f32_e32 v43, v43, v43
	v_cvt_pk_f16_f32 v40, v44, v40
	v_add_co_u32_e32 v44, vcc, s81, v176
	v_pk_fma_f32 v[36:37], v[144:145], v[182:183], v[36:37] op_sel_hi:[1,0,1] neg_lo:[1,0,0] neg_hi:[1,0,0]
	v_pk_fma_f32 v[38:39], v[116:117], v[182:183], v[38:39] op_sel_hi:[1,0,1]
	v_pk_fma_f32 v[34:35], v[34:35], v[124:125], v[138:139] op_sel_hi:[1,0,1]
	v_pk_fma_f32 v[32:33], v[32:33], v[124:125], v[136:137] op_sel_hi:[1,0,1]
	v_max_f32_e32 v123, 0, v142
	v_cvt_pk_f16_f32 v41, v41, v42
	v_cvt_pk_f16_f32 v42, v50, v45
	v_cvt_pk_f16_f32 v43, v46, v43
	v_addc_co_u32_e32 v45, vcc, 0, v177, vcc
	v_pk_fma_f32 v[38:39], v[38:39], v[124:125], v[150:151] op_sel_hi:[1,0,1]
	v_pk_fma_f32 v[36:37], v[36:37], v[124:125], v[148:149] op_sel_hi:[1,0,1]
	v_max_f32_e32 v32, 0, v32
	v_max_f32_e32 v33, 0, v33
	v_max_f32_e32 v34, 0, v34
	v_mul_f32_e32 v123, v123, v123
	flat_store_dwordx4 v[44:45], v[40:43] sc1
	v_max_f32_e32 v36, 0, v36
	v_max_f32_e32 v35, 0, v35
	v_mul_f32_e32 v40, v32, v32
	v_max_f32_e32 v32, 0, v37
	v_mul_f32_e32 v37, v33, v33
	v_max_f32_e32 v33, 0, v38
	v_mul_f32_e32 v38, v34, v34
	v_max_f32_e32 v34, 0, v39
	v_pk_fma_f32 v[24:25], v[128:129], v[180:181], v[24:25] op_sel_hi:[1,0,1] neg_lo:[1,0,0] neg_hi:[1,0,0]
	v_mul_f32_e32 v36, v36, v36
	v_mul_f32_e32 v32, v32, v32
	v_mul_f32_e32 v33, v33, v33
	v_mul_f32_e32 v34, v34, v34
	v_mul_f32_e32 v35, v35, v35
	v_pk_fma_f32 v[28:29], v[132:133], v[180:181], v[28:29] op_sel_hi:[1,0,1] neg_lo:[1,0,0] neg_hi:[1,0,0]
	v_pk_fma_f32 v[26:27], v[178:179], v[180:181], v[26:27] op_sel_hi:[1,0,1]
	v_pk_fma_f32 v[24:25], v[24:25], v[122:123], v[152:153] op_sel_hi:[1,0,1]
	v_lshl_add_u64 v[48:49], v[176:177], 0, s[22:23]
	v_cvt_pk_f16_f32 v32, v36, v32
	v_cvt_pk_f16_f32 v33, v33, v34
	v_cvt_pk_f16_f32 v34, v40, v37
	v_cvt_pk_f16_f32 v35, v38, v35
	v_pk_fma_f32 v[30:31], v[134:135], v[180:181], v[30:31] op_sel_hi:[1,0,1]
	v_pk_fma_f32 v[28:29], v[28:29], v[122:123], v[156:157] op_sel_hi:[1,0,1]
	v_pk_fma_f32 v[26:27], v[26:27], v[122:123], v[154:155] op_sel_hi:[1,0,1]
	v_max_f32_e32 v24, 0, v24
	flat_store_dwordx4 v[48:49], v[32:35] offset:256 sc1
	v_pk_fma_f32 v[30:31], v[30:31], v[122:123], v[158:159] op_sel_hi:[1,0,1]
	v_max_f32_e32 v28, 0, v28
	v_mul_f32_e32 v34, v24, v24
	v_max_f32_e32 v24, 0, v29
	v_max_f32_e32 v25, 0, v25
	v_max_f32_e32 v26, 0, v26
	v_mul_f32_e32 v28, v28, v28
	v_mul_f32_e32 v24, v24, v24
	v_mul_f32_e32 v29, v25, v25
	v_max_f32_e32 v25, 0, v30
	v_mul_f32_e32 v30, v26, v26
	v_max_f32_e32 v26, 0, v31
	v_max_f32_e32 v27, 0, v27
	v_pk_fma_f32 v[16:17], v[140:141], v[180:181], v[16:17] op_sel_hi:[1,0,1] neg_lo:[1,0,0] neg_hi:[1,0,0]
	v_pk_fma_f32 v[18:19], v[112:113], v[180:181], v[18:19] op_sel_hi:[1,0,1]
;     __device__ __forceinline__ void operator()(const f32x4 (&acc)[2][2][4][2], const Unit& u, int wr, int wc, int fr, int fq) const {
;     ...
;                 for (int m = 0; m < 4; ++m) { const int row = row0 + ai * HALF + m * 16; bf16_t* rowp = O + (size_t)row * ldc + col0;
;                     const float mean = mean8[ai][m], rstd = rstd8[ai][m];
; #pragma unroll
;                     for (int bj = 0; bj < 2; ++bj) { f32x4 v0 = acc[ai][bj][m][0], v1 = acc[ai][bj][m][1];
;                         if (F == 1) { v0 = (v0 - c1v[bj][0] * mean) * rstd + c2v[bj][0]; v1 = (v1 - c1v[bj][1] * mean) * rstd + c2v[bj][1]; }
;                         if (kind == 1) {
; #pragma unroll
;                             for (int e = 0; e < 4; ++e) { float a = fmaxf(v0[e], 0.f), b_ = fmaxf(v1[e], 0.f); v0[e] = a * a; v1[e] = b_ * b_; } }
;                         u32x4 w; w.x = pk16(v0[0], v0[1]); w.y = pk16(v0[2], v0[3]); w.z = pk16(v1[0], v1[1]); w.w = pk16(v1[2], v1[3]);
;                         *(u32x4*)(rowp + bj * HALF) = w; } }
	v_mul_f32_e32 v25, v25, v25
	v_mul_f32_e32 v26, v26, v26
	v_mul_f32_e32 v27, v27, v27
	v_cvt_pk_f16_f32 v24, v28, v24
	v_add_co_u32_e32 v28, vcc, s82, v176
	v_pk_fma_f32 v[20:21], v[144:145], v[180:181], v[20:21] op_sel_hi:[1,0,1] neg_lo:[1,0,0] neg_hi:[1,0,0]
	v_pk_fma_f32 v[22:23], v[116:117], v[180:181], v[22:23] op_sel_hi:[1,0,1]
	v_pk_fma_f32 v[18:19], v[18:19], v[122:123], v[138:139] op_sel_hi:[1,0,1]
	v_pk_fma_f32 v[16:17], v[16:17], v[122:123], v[136:137] op_sel_hi:[1,0,1]
	v_max_f32_e32 v121, 0, v146
	v_cvt_pk_f16_f32 v25, v25, v26
	v_cvt_pk_f16_f32 v26, v34, v29
	v_cvt_pk_f16_f32 v27, v30, v27
	v_addc_co_u32_e32 v29, vcc, 0, v177, vcc
	v_pk_fma_f32 v[22:23], v[22:23], v[122:123], v[150:151] op_sel_hi:[1,0,1]
	v_pk_fma_f32 v[20:21], v[20:21], v[122:123], v[148:149] op_sel_hi:[1,0,1]
	v_max_f32_e32 v16, 0, v16
	v_max_f32_e32 v17, 0, v17
	v_max_f32_e32 v18, 0, v18
	v_mul_f32_e32 v121, v121, v121
	flat_store_dwordx4 v[28:29], v[24:27] sc1
	v_max_f32_e32 v20, 0, v20
	v_max_f32_e32 v19, 0, v19
	v_mul_f32_e32 v24, v16, v16
	v_max_f32_e32 v16, 0, v21
	v_mul_f32_e32 v21, v17, v17
	v_max_f32_e32 v17, 0, v22
	v_mul_f32_e32 v22, v18, v18
	v_max_f32_e32 v18, 0, v23
	v_pk_fma_f32 v[8:9], v[128:129], v[130:131], v[8:9] op_sel_hi:[1,0,1] neg_lo:[1,0,0] neg_hi:[1,0,0]
	v_mul_f32_e32 v20, v20, v20
	v_mul_f32_e32 v16, v16, v16
	v_mul_f32_e32 v17, v17, v17
	v_mul_f32_e32 v18, v18, v18
	v_mul_f32_e32 v19, v19, v19
	v_pk_fma_f32 v[12:13], v[132:133], v[130:131], v[12:13] op_sel_hi:[1,0,1] neg_lo:[1,0,0] neg_hi:[1,0,0]
	v_pk_fma_f32 v[10:11], v[178:179], v[130:131], v[10:11] op_sel_hi:[1,0,1]
	v_pk_fma_f32 v[8:9], v[8:9], v[120:121], v[152:153] op_sel_hi:[1,0,1]
	v_lshl_add_u64 v[32:33], v[176:177], 0, s[24:25]
	v_cvt_pk_f16_f32 v16, v20, v16
	v_cvt_pk_f16_f32 v17, v17, v18
	v_cvt_pk_f16_f32 v18, v24, v21
	v_cvt_pk_f16_f32 v19, v22, v19
	v_pk_fma_f32 v[14:15], v[134:135], v[130:131], v[14:15] op_sel_hi:[1,0,1]
	v_pk_fma_f32 v[12:13], v[12:13], v[120:121], v[156:157] op_sel_hi:[1,0,1]
	v_pk_fma_f32 v[10:11], v[10:11], v[120:121], v[154:155] op_sel_hi:[1,0,1]
	v_max_f32_e32 v8, 0, v8
	flat_store_dwordx4 v[32:33], v[16:19] offset:256 sc1
	v_pk_fma_f32 v[14:15], v[14:15], v[120:121], v[158:159] op_sel_hi:[1,0,1]
	v_max_f32_e32 v12, 0, v12
	v_mul_f32_e32 v18, v8, v8
	v_max_f32_e32 v8, 0, v13
	v_max_f32_e32 v9, 0, v9
	v_max_f32_e32 v10, 0, v10
	v_mul_f32_e32 v12, v12, v12
	v_mul_f32_e32 v8, v8, v8
	v_mul_f32_e32 v13, v9, v9
	v_max_f32_e32 v9, 0, v14
	v_mul_f32_e32 v14, v10, v10
	v_max_f32_e32 v10, 0, v15
	v_max_f32_e32 v11, 0, v11
	v_pk_fma_f32 v[0:1], v[140:141], v[130:131], v[0:1] op_sel_hi:[1,0,1] neg_lo:[1,0,0] neg_hi:[1,0,0]
	v_pk_fma_f32 v[2:3], v[112:113], v[130:131], v[2:3] op_sel_hi:[1,0,1]
	v_mul_f32_e32 v9, v9, v9
	v_mul_f32_e32 v10, v10, v10
	v_mul_f32_e32 v11, v11, v11
	v_cvt_pk_f16_f32 v8, v12, v8
	v_add_co_u32_e32 v12, vcc, s83, v176
	v_pk_fma_f32 v[4:5], v[144:145], v[130:131], v[4:5] op_sel_hi:[1,0,1] neg_lo:[1,0,0] neg_hi:[1,0,0]
	v_pk_fma_f32 v[6:7], v[116:117], v[130:131], v[6:7] op_sel_hi:[1,0,1]
	v_pk_fma_f32 v[2:3], v[2:3], v[120:121], v[138:139] op_sel_hi:[1,0,1]
	v_pk_fma_f32 v[0:1], v[0:1], v[120:121], v[136:137] op_sel_hi:[1,0,1]
	v_cvt_pk_f16_f32 v9, v9, v10
	v_cvt_pk_f16_f32 v10, v18, v13
	v_cvt_pk_f16_f32 v11, v14, v11
	v_addc_co_u32_e32 v13, vcc, 0, v177, vcc
	v_pk_fma_f32 v[6:7], v[6:7], v[120:121], v[150:151] op_sel_hi:[1,0,1]
	v_pk_fma_f32 v[4:5], v[4:5], v[120:121], v[148:149] op_sel_hi:[1,0,1]
	v_max_f32_e32 v0, 0, v0
	v_max_f32_e32 v1, 0, v1
	v_max_f32_e32 v2, 0, v2
	flat_store_dwordx4 v[12:13], v[8:11] sc1
	v_max_f32_e32 v4, 0, v4
	v_max_f32_e32 v3, 0, v3
	v_mul_f32_e32 v8, v0, v0
	v_max_f32_e32 v0, 0, v5
	v_mul_f32_e32 v5, v1, v1
	v_max_f32_e32 v1, 0, v6
	v_mul_f32_e32 v6, v2, v2
	v_max_f32_e32 v2, 0, v7
	v_mul_f32_e32 v4, v4, v4
	v_mul_f32_e32 v0, v0, v0
	v_mul_f32_e32 v1, v1, v1
	v_mul_f32_e32 v2, v2, v2
	v_mul_f32_e32 v3, v3, v3
	v_cvt_pk_f16_f32 v208, v121, v125
	v_cvt_pk_f16_f32 v210, v123, v127
	v_lshl_add_u64 v[16:17], v[176:177], 0, s[26:27]
	v_cvt_pk_f16_f32 v0, v4, v0
	v_cvt_pk_f16_f32 v1, v1, v2
	v_cvt_pk_f16_f32 v2, v8, v5
	v_cvt_pk_f16_f32 v3, v6, v3
	s_andn2_b64 vcc, exec, s[6:7]
	s_mov_b64 s[6:7], -1
	flat_store_dwordx4 v[176:177], v[208:211] offset:256 sc1
	flat_store_dwordx4 v[16:17], v[0:3] offset:256 sc1
	s_cbranch_vccnz .LBB0_569
	s_andn2_b64 vcc, exec, s[0:1]
	s_cbranch_vccnz .LBB0_568
	s_barrier
	s_branch .LBB0_568

;     __device__ __forceinline__ void operator()(const f32x4 (&acc)[2][2][4][2], const Unit& u, int wr, int wc, int fr, int fq) const {
;     ...
;             const int col0 = u.pn * BM + wc * 32 + 8 * fq;
;             f32x4 c1v[2][2], c2v[2][2];
;             if (F == 1) {
; #pragma unroll
;                 for (int bj = 0; bj < 2; ++bj)
; #pragma unroll
;                     for (int n = 0; n < 2; ++n) { c1v[bj][n] = *(const f32x4*)(c1 + col0 + bj * HALF + 4 * n); c2v[bj][n] = *(const f32x4*)(c2 + col0 + bj * HALF + 4 * n); } }
;             float mean8[2][4], rstd8[2][4];
; #pragma unroll
;             for (int ai = 0; ai < 2; ++ai)
; #pragma unroll
;                 for (int m = 0; m < 4; ++m) { mean8[ai][m] = 0.f; rstd8[ai][m] = 1.f; if (F == 1) row_stats(row0 + ai * HALF + m * 16, mean8[ai][m], rstd8[ai][m]); }
; #pragma unroll
;             for (int ai = 0; ai < 2; ++ai)
; #pragma unroll
;                 for (int m = 0; m < 4; ++m) { const int row = row0 + ai * HALF + m * 16; bf16_t* rowp = O + (size_t)row * ldc + col0;
;                     const float mean = mean8[ai][m], rstd = rstd8[ai][m];
; #pragma unroll
;                     for (int bj = 0; bj < 2; ++bj) { f32x4 v0 = acc[ai][bj][m][0], v1 = acc[ai][bj][m][1];
;                         if (F == 1) { v0 = (v0 - c1v[bj][0] * mean) * rstd + c2v[bj][0]; v1 = (v1 - c1v[bj][1] * mean) * rstd + c2v[bj][1]; }
.LBB0_1170:
	v_lshl_or_b32 v136, s71, 8, v197
	v_lshl_add_u32 v186, s40, 8, v193
	v_ashrrev_i32_e32 v137, 31, v136
	v_lshlrev_b32_e32 v142, 1, v186
	v_lshlrev_b64 v[138:139], 2, v[136:137]
	v_ashrrev_i32_e32 v143, 31, v142
	v_lshl_add_u64 v[140:141], s[12:13], 0, v[138:139]
	v_lshl_add_u64 v[144:145], v[142:143], 2, s[10:11]
	flat_load_dwordx4 v[132:135], v[140:141]
	flat_load_dwordx4 v[128:131], v[140:141] offset:16
	flat_load_dwordx2 v[178:179], v[144:145]
	flat_load_dwordx2 v[180:181], v[144:145] offset:128
	flat_load_dwordx2 v[182:183], v[144:145] offset:256
	flat_load_dwordx2 v[184:185], v[144:145] offset:384
	v_add_u32_e32 v144, 0x100, v142
	v_ashrrev_i32_e32 v145, 31, v144
	v_add_u32_e32 v146, 0x120, v142
	v_add_u32_e32 v148, 0x140, v142
	v_add_u32_e32 v142, 0x160, v142
	v_lshl_add_u64 v[144:145], v[144:145], 2, s[10:11]
	v_ashrrev_i32_e32 v147, 31, v146
	v_ashrrev_i32_e32 v149, 31, v148
	v_ashrrev_i32_e32 v143, 31, v142
	v_lshl_add_u64 v[146:147], v[146:147], 2, s[10:11]
	v_lshl_add_u64 v[148:149], v[148:149], 2, s[10:11]
	v_lshl_add_u64 v[142:143], v[142:143], 2, s[10:11]
	flat_load_dwordx2 v[202:203], v[144:145]
	flat_load_dwordx2 v[208:209], v[146:147]
	flat_load_dwordx2 v[210:211], v[148:149]
	flat_load_dwordx2 v[212:213], v[142:143]
	v_lshl_add_u64 v[138:139], s[14:15], 0, v[138:139]
	flat_load_dwordx4 v[156:159], v[138:139]
	flat_load_dwordx4 v[152:155], v[138:139] offset:16
	v_ashrrev_i32_e32 v187, 31, v186
	flat_load_dwordx4 v[144:147], v[140:141] offset:512
	v_lshlrev_b64 v[142:143], 14, v[186:187]
	v_lshlrev_b64 v[190:191], 1, v[136:137]
	v_lshl_add_u64 v[176:177], s[8:9], 0, v[142:143]
	flat_load_dwordx4 v[140:143], v[140:141] offset:528
	s_nop 0
	flat_load_dwordx4 v[148:151], v[138:139] offset:512
	s_nop 0
	flat_load_dwordx4 v[136:139], v[138:139] offset:528
	v_lshl_add_u64 v[176:177], v[176:177], 0, v[190:191]
	s_waitcnt vmcnt(0) lgkmcnt(0)
	v_pk_mul_f32 v[214:215], v[178:179], s[20:21] op_sel_hi:[1,0]
	s_nop 0
	v_fma_f32 v187, -v214, v214, v215
	v_pk_mul_f32 v[216:217], v[180:181], s[20:21] op_sel_hi:[1,0]
	v_pk_mul_f32 v[188:189], v[184:185], s[20:21] op_sel_hi:[1,0]
	v_xor_b32_e32 v179, 0x80000000, v131
	v_xor_b32_e32 v178, 0x80000000, v130
	v_fma_f32 v218, -v188, v188, v189
	v_pk_mul_f32 v[194:195], v[182:183], s[20:21] op_sel_hi:[1,0]
	v_fma_f32 v192, -v216, v216, v217
	v_xor_b32_e32 v135, 0x80000000, v135
	v_xor_b32_e32 v134, 0x80000000, v134
	v_fma_f32 v201, -v194, v194, v195
	v_pk_fma_f32 v[104:105], v[128:129], v[216:217], v[104:105] op_sel_hi:[1,0,1] neg_lo:[1,0,0] neg_hi:[1,0,0]
	v_pk_mul_f32 v[184:185], v[202:203], s[20:21] op_sel_hi:[1,0]
	v_pk_mul_f32 v[182:183], v[208:209], s[20:21] op_sel_hi:[1,0]
	v_pk_mul_f32 v[180:181], v[210:211], s[20:21] op_sel_hi:[1,0]
	v_pk_fma_f32 v[210:211], v[128:129], v[214:215], v[120:121] op_sel_hi:[1,0,1] neg_lo:[1,0,0] neg_hi:[1,0,0]
	v_max_f32_e32 v120, 0, v187
	v_add_f32_e32 v120, 0x3727c5ac, v120
	v_pk_mul_f32 v[130:131], v[212:213], s[20:21] op_sel_hi:[1,0]
	v_pk_fma_f32 v[212:213], v[178:179], v[214:215], v[122:123] op_sel_hi:[1,0,1]
	v_max_f32_e32 v123, 0, v218
	v_rsq_f32_e32 v218, v120
	v_pk_fma_f32 v[202:203], v[132:133], v[214:215], v[124:125] op_sel_hi:[1,0,1] neg_lo:[1,0,0] neg_hi:[1,0,0]
	v_max_f32_e32 v121, 0, v192
	v_fma_f32 v125, -v182, v182, v183
	v_pk_fma_f32 v[208:209], v[134:135], v[214:215], v[126:127] op_sel_hi:[1,0,1]
	v_fma_f32 v124, -v184, v184, v185
	v_add_f32_e32 v121, 0x3727c5ac, v121
	v_max_f32_e32 v125, 0, v125
	v_max_f32_e32 v124, 0, v124
	v_rsq_f32_e32 v220, v121
	v_add_f32_e32 v121, 0x3727c5ac, v125
	v_pk_fma_f32 v[208:209], v[208:209], v[218:219], v[158:159] op_sel_hi:[1,0,1]
	v_pk_fma_f32 v[202:203], v[202:203], v[218:219], v[156:157] op_sel_hi:[1,0,1]
	v_pk_fma_f32 v[212:213], v[212:213], v[218:219], v[154:155] op_sel_hi:[1,0,1]
	v_max_f32_e32 v122, 0, v201
	v_fma_f32 v127, -v130, v130, v131
	v_add_f32_e32 v120, 0x3727c5ac, v124
	v_rsq_f32_e32 v124, v121
	v_max_f32_e32 v121, 0, v202
	v_max_f32_e32 v125, 0, v203
	v_max_f32_e32 v187, 0, v208
	v_max_f32_e32 v201, 0, v212
	v_max_f32_e32 v202, 0, v209
	v_max_f32_e32 v203, 0, v213
	v_add_f32_e32 v123, 0x3727c5ac, v123
	v_max_f32_e32 v127, 0, v127
	v_pk_fma_f32 v[210:211], v[210:211], v[218:219], v[152:153] op_sel_hi:[1,0,1]
	v_mul_f32_e32 v187, v187, v187
	v_mul_f32_e32 v201, v201, v201
	v_mul_f32_e32 v202, v202, v202
	v_mul_f32_e32 v203, v203, v203
	v_rsq_f32_e32 v192, v123
	v_add_f32_e32 v123, 0x3727c5ac, v127
	v_max_f32_e32 v127, 0, v211
	v_cvt_pk_f16_f32 v209, v187, v202
	v_cvt_pk_f16_f32 v211, v201, v203
	v_pk_fma_f32 v[202:203], v[144:145], v[214:215], v[116:117] op_sel_hi:[1,0,1] neg_lo:[1,0,0] neg_hi:[1,0,0]
	v_fma_f32 v126, -v180, v180, v181
	v_xor_b32_e32 v117, 0x80000000, v147
	v_xor_b32_e32 v116, 0x80000000, v146
	v_pk_fma_f32 v[146:147], v[202:203], v[218:219], v[148:149] op_sel_hi:[1,0,1]
	v_pk_fma_f32 v[202:203], v[140:141], v[214:215], v[112:113] op_sel_hi:[1,0,1] neg_lo:[1,0,0] neg_hi:[1,0,0]
	v_xor_b32_e32 v113, 0x80000000, v143
	v_xor_b32_e32 v112, 0x80000000, v142
	v_add_f32_e32 v122, 0x3727c5ac, v122
	v_max_f32_e32 v126, 0, v126
	v_pk_fma_f32 v[114:115], v[112:113], v[214:215], v[114:115] op_sel_hi:[1,0,1]
	v_rsq_f32_e32 v222, v122
	v_add_f32_e32 v122, 0x3727c5ac, v126
	v_rsq_f32_e32 v126, v120
	v_rsq_f32_e32 v120, v123
	v_max_f32_e32 v123, 0, v210
	v_pk_fma_f32 v[114:115], v[114:115], v[218:219], v[138:139] op_sel_hi:[1,0,1]
	v_mul_f32_e32 v121, v121, v121
	v_mul_f32_e32 v123, v123, v123
	v_mul_f32_e32 v125, v125, v125
	v_mul_f32_e32 v127, v127, v127
	v_pk_fma_f32 v[118:119], v[116:117], v[214:215], v[118:119] op_sel_hi:[1,0,1]
	v_max_f32_e32 v114, 0, v114
;     __device__ __forceinline__ void operator()(const f32x4 (&acc)[2][2][4][2], const Unit& u, int wr, int wc, int fr, int fq) const {
;     ...
;                 for (int m = 0; m < 4; ++m) { const int row = row0 + ai * HALF + m * 16; bf16_t* rowp = O + (size_t)row * ldc + col0;
;                     const float mean = mean8[ai][m], rstd = rstd8[ai][m];
; #pragma unroll
;                     for (int bj = 0; bj < 2; ++bj) { f32x4 v0 = acc[ai][bj][m][0], v1 = acc[ai][bj][m][1];
;                         if (F == 1) { v0 = (v0 - c1v[bj][0] * mean) * rstd + c2v[bj][0]; v1 = (v1 - c1v[bj][1] * mean) * rstd + c2v[bj][1]; }
;                         if (kind == 1) {
; #pragma unroll
;                             for (int e = 0; e < 4; ++e) { float a = fmaxf(v0[e], 0.f), b_ = fmaxf(v1[e], 0.f); v0[e] = a * a; v1[e] = b_ * b_; } }
;                         u32x4 w; w.x = pk16(v0[0], v0[1]); w.y = pk16(v0[2], v0[3]); w.z = pk16(v1[0], v1[1]); w.w = pk16(v1[2], v1[3]);
;                         *(u32x4*)(rowp + bj * HALF) = w; } }
	v_max_f32_e32 v115, 0, v115
	v_cvt_pk_f16_f32 v208, v121, v125
	v_cvt_pk_f16_f32 v210, v123, v127
	v_pk_fma_f32 v[118:119], v[118:119], v[218:219], v[150:151] op_sel_hi:[1,0,1]
	v_mul_f32_e32 v114, v114, v114
	v_mul_f32_e32 v115, v115, v115
	v_pk_fma_f32 v[106:107], v[178:179], v[216:217], v[106:107] op_sel_hi:[1,0,1]
	flat_store_dwordx4 v[176:177], v[208:211] sc1
	v_max_f32_e32 v118, 0, v118
	v_max_f32_e32 v119, 0, v119
	v_cvt_pk_f16_f32 v211, v114, v115
	v_or_b32_e32 v114, 16, v186
	v_pk_fma_f32 v[108:109], v[132:133], v[216:217], v[108:109] op_sel_hi:[1,0,1] neg_lo:[1,0,0] neg_hi:[1,0,0]
	v_pk_fma_f32 v[110:111], v[134:135], v[216:217], v[110:111] op_sel_hi:[1,0,1]
	v_pk_fma_f32 v[106:107], v[106:107], v[220:221], v[154:155] op_sel_hi:[1,0,1]
	v_pk_fma_f32 v[104:105], v[104:105], v[220:221], v[152:153] op_sel_hi:[1,0,1]
	v_mul_f32_e32 v118, v118, v118
	v_mul_f32_e32 v119, v119, v119
	v_ashrrev_i32_e32 v115, 31, v114
	v_pk_fma_f32 v[110:111], v[110:111], v[220:221], v[158:159] op_sel_hi:[1,0,1]
	v_pk_fma_f32 v[108:109], v[108:109], v[220:221], v[156:157] op_sel_hi:[1,0,1]
	v_max_f32_e32 v104, 0, v104
	v_max_f32_e32 v105, 0, v105
	v_max_f32_e32 v106, 0, v106
	v_cvt_pk_f16_f32 v209, v118, v119
	v_lshlrev_b64 v[114:115], 14, v[114:115]
	v_max_f32_e32 v108, 0, v108
	v_mul_f32_e32 v118, v104, v104
	v_max_f32_e32 v104, 0, v109
	v_mul_f32_e32 v109, v105, v105
	v_max_f32_e32 v105, 0, v110
	v_mul_f32_e32 v110, v106, v106
	v_max_f32_e32 v106, 0, v111
	v_max_f32_e32 v107, 0, v107
	v_pk_fma_f32 v[96:97], v[140:141], v[216:217], v[96:97] op_sel_hi:[1,0,1] neg_lo:[1,0,0] neg_hi:[1,0,0]
	v_pk_fma_f32 v[98:99], v[112:113], v[216:217], v[98:99] op_sel_hi:[1,0,1]
	v_lshl_add_u64 v[114:115], s[8:9], 0, v[114:115]
	v_mul_f32_e32 v108, v108, v108
	v_mul_f32_e32 v104, v104, v104
	v_mul_f32_e32 v105, v105, v105
	v_mul_f32_e32 v106, v106, v106
	v_mul_f32_e32 v107, v107, v107
	v_pk_fma_f32 v[100:101], v[144:145], v[216:217], v[100:101] op_sel_hi:[1,0,1] neg_lo:[1,0,0] neg_hi:[1,0,0]
	v_pk_fma_f32 v[102:103], v[116:117], v[216:217], v[102:103] op_sel_hi:[1,0,1]
	v_pk_fma_f32 v[98:99], v[98:99], v[220:221], v[138:139] op_sel_hi:[1,0,1]
	v_pk_fma_f32 v[96:97], v[96:97], v[220:221], v[136:137] op_sel_hi:[1,0,1]
	v_lshl_add_u64 v[114:115], v[114:115], 0, v[190:191]
	v_cvt_pk_f16_f32 v104, v108, v104
	v_cvt_pk_f16_f32 v105, v105, v106
	v_cvt_pk_f16_f32 v106, v118, v109
	v_cvt_pk_f16_f32 v107, v110, v107
	v_pk_fma_f32 v[102:103], v[102:103], v[220:221], v[150:151] op_sel_hi:[1,0,1]
	v_pk_fma_f32 v[100:101], v[100:101], v[220:221], v[148:149] op_sel_hi:[1,0,1]
	v_max_f32_e32 v96, 0, v96
	v_max_f32_e32 v97, 0, v97
	v_max_f32_e32 v98, 0, v98
	flat_store_dwordx4 v[114:115], v[104:107] sc1
	v_max_f32_e32 v100, 0, v100
	v_max_f32_e32 v99, 0, v99
	v_mul_f32_e32 v104, v96, v96
	v_max_f32_e32 v96, 0, v101
	v_mul_f32_e32 v101, v97, v97
	v_max_f32_e32 v97, 0, v102
	v_mul_f32_e32 v102, v98, v98
	v_max_f32_e32 v98, 0, v103
	v_mul_f32_e32 v100, v100, v100
	v_mul_f32_e32 v96, v96, v96
	v_mul_f32_e32 v97, v97, v97
	v_mul_f32_e32 v98, v98, v98
	v_mul_f32_e32 v99, v99, v99
	v_cvt_pk_f16_f32 v96, v100, v96
	v_cvt_pk_f16_f32 v97, v97, v98
	v_cvt_pk_f16_f32 v98, v104, v101
	v_cvt_pk_f16_f32 v99, v102, v99
	v_pk_fma_f32 v[88:89], v[128:129], v[194:195], v[88:89] op_sel_hi:[1,0,1] neg_lo:[1,0,0] neg_hi:[1,0,0]
	v_pk_fma_f32 v[90:91], v[178:179], v[194:195], v[90:91] op_sel_hi:[1,0,1]
	flat_store_dwordx4 v[114:115], v[96:99] offset:256 sc1
	v_pk_fma_f32 v[92:93], v[132:133], v[194:195], v[92:93] op_sel_hi:[1,0,1] neg_lo:[1,0,0] neg_hi:[1,0,0]
	v_pk_fma_f32 v[94:95], v[134:135], v[194:195], v[94:95] op_sel_hi:[1,0,1]
	v_or_b32_e32 v96, 32, v186
	v_pk_fma_f32 v[90:91], v[90:91], v[222:223], v[154:155] op_sel_hi:[1,0,1]
	v_pk_fma_f32 v[88:89], v[88:89], v[222:223], v[152:153] op_sel_hi:[1,0,1]
	v_ashrrev_i32_e32 v97, 31, v96
	v_pk_fma_f32 v[94:95], v[94:95], v[222:223], v[158:159] op_sel_hi:[1,0,1]
	v_pk_fma_f32 v[92:93], v[92:93], v[222:223], v[156:157] op_sel_hi:[1,0,1]
	v_max_f32_e32 v88, 0, v88
	v_max_f32_e32 v89, 0, v89
	v_max_f32_e32 v90, 0, v90
	v_lshlrev_b64 v[96:97], 14, v[96:97]
	v_max_f32_e32 v92, 0, v92
	v_mul_f32_e32 v98, v88, v88
	v_max_f32_e32 v88, 0, v93
	v_mul_f32_e32 v93, v89, v89
	v_max_f32_e32 v89, 0, v94
	v_mul_f32_e32 v94, v90, v90
	v_max_f32_e32 v90, 0, v95
	v_max_f32_e32 v91, 0, v91
	v_pk_fma_f32 v[80:81], v[140:141], v[194:195], v[80:81] op_sel_hi:[1,0,1] neg_lo:[1,0,0] neg_hi:[1,0,0]
	v_pk_fma_f32 v[82:83], v[112:113], v[194:195], v[82:83] op_sel_hi:[1,0,1]
	v_lshl_add_u64 v[96:97], s[8:9], 0, v[96:97]
	v_mul_f32_e32 v92, v92, v92
	v_mul_f32_e32 v88, v88, v88
	v_mul_f32_e32 v89, v89, v89
	v_mul_f32_e32 v90, v90, v90
	v_mul_f32_e32 v91, v91, v91
	v_pk_fma_f32 v[84:85], v[144:145], v[194:195], v[84:85] op_sel_hi:[1,0,1] neg_lo:[1,0,0] neg_hi:[1,0,0]
	v_pk_fma_f32 v[86:87], v[116:117], v[194:195], v[86:87] op_sel_hi:[1,0,1]
	v_pk_fma_f32 v[82:83], v[82:83], v[222:223], v[138:139] op_sel_hi:[1,0,1]
	v_pk_fma_f32 v[80:81], v[80:81], v[222:223], v[136:137] op_sel_hi:[1,0,1]
	v_lshl_add_u64 v[96:97], v[96:97], 0, v[190:191]
	v_cvt_pk_f16_f32 v88, v92, v88
	v_cvt_pk_f16_f32 v89, v89, v90
	v_cvt_pk_f16_f32 v90, v98, v93
	v_cvt_pk_f16_f32 v91, v94, v91
	v_pk_fma_f32 v[86:87], v[86:87], v[222:223], v[150:151] op_sel_hi:[1,0,1]
	v_pk_fma_f32 v[84:85], v[84:85], v[222:223], v[148:149] op_sel_hi:[1,0,1]
	v_max_f32_e32 v80, 0, v80
	v_max_f32_e32 v81, 0, v81
	v_max_f32_e32 v82, 0, v82
	flat_store_dwordx4 v[96:97], v[88:91] sc1
	v_max_f32_e32 v84, 0, v84
	v_max_f32_e32 v83, 0, v83
	v_mul_f32_e32 v88, v80, v80
	v_max_f32_e32 v80, 0, v85
	v_mul_f32_e32 v85, v81, v81
	v_max_f32_e32 v81, 0, v86
;     __device__ __forceinline__ void operator()(const f32x4 (&acc)[2][2][4][2], const Unit& u, int wr, int wc, int fr, int fq) const {
;     ...
;                 for (int m = 0; m < 4; ++m) { const int row = row0 + ai * HALF + m * 16; bf16_t* rowp = O + (size_t)row * ldc + col0;
;                     const float mean = mean8[ai][m], rstd = rstd8[ai][m];
; #pragma unroll
;                     for (int bj = 0; bj < 2; ++bj) { f32x4 v0 = acc[ai][bj][m][0], v1 = acc[ai][bj][m][1];
;                         if (F == 1) { v0 = (v0 - c1v[bj][0] * mean) * rstd + c2v[bj][0]; v1 = (v1 - c1v[bj][1] * mean) * rstd + c2v[bj][1]; }
;                         if (kind == 1) {
; #pragma unroll
;                             for (int e = 0; e < 4; ++e) { float a = fmaxf(v0[e], 0.f), b_ = fmaxf(v1[e], 0.f); v0[e] = a * a; v1[e] = b_ * b_; } }
;                         u32x4 w; w.x = pk16(v0[0], v0[1]); w.y = pk16(v0[2], v0[3]); w.z = pk16(v1[0], v1[1]); w.w = pk16(v1[2], v1[3]);
;                         *(u32x4*)(rowp + bj * HALF) = w; } }
	v_mul_f32_e32 v86, v82, v82
	v_max_f32_e32 v82, 0, v87
	v_mul_f32_e32 v84, v84, v84
	v_mul_f32_e32 v80, v80, v80
	v_mul_f32_e32 v81, v81, v81
	v_mul_f32_e32 v82, v82, v82
	v_mul_f32_e32 v83, v83, v83
	v_cvt_pk_f16_f32 v80, v84, v80
	v_cvt_pk_f16_f32 v81, v81, v82
	v_cvt_pk_f16_f32 v82, v88, v85
	v_cvt_pk_f16_f32 v83, v86, v83
	v_pk_fma_f32 v[72:73], v[128:129], v[188:189], v[72:73] op_sel_hi:[1,0,1] neg_lo:[1,0,0] neg_hi:[1,0,0]
	v_pk_fma_f32 v[74:75], v[178:179], v[188:189], v[74:75] op_sel_hi:[1,0,1]
	flat_store_dwordx4 v[96:97], v[80:83] offset:256 sc1
	v_pk_fma_f32 v[76:77], v[132:133], v[188:189], v[76:77] op_sel_hi:[1,0,1] neg_lo:[1,0,0] neg_hi:[1,0,0]
	v_pk_fma_f32 v[78:79], v[134:135], v[188:189], v[78:79] op_sel_hi:[1,0,1]
	v_or_b32_e32 v80, 48, v186
	v_pk_fma_f32 v[74:75], v[74:75], v[192:193], v[154:155] op_sel_hi:[1,0,1]
	v_pk_fma_f32 v[72:73], v[72:73], v[192:193], v[152:153] op_sel_hi:[1,0,1]
	v_ashrrev_i32_e32 v81, 31, v80
	v_pk_fma_f32 v[78:79], v[78:79], v[192:193], v[158:159] op_sel_hi:[1,0,1]
	v_pk_fma_f32 v[76:77], v[76:77], v[192:193], v[156:157] op_sel_hi:[1,0,1]
	v_max_f32_e32 v72, 0, v72
	v_max_f32_e32 v73, 0, v73
	v_max_f32_e32 v74, 0, v74
	v_lshlrev_b64 v[80:81], 14, v[80:81]
	v_max_f32_e32 v76, 0, v76
	v_mul_f32_e32 v82, v72, v72
	v_max_f32_e32 v72, 0, v77
	v_mul_f32_e32 v77, v73, v73
	v_max_f32_e32 v73, 0, v78
	v_mul_f32_e32 v78, v74, v74
	v_max_f32_e32 v74, 0, v79
	v_max_f32_e32 v75, 0, v75
	v_pk_fma_f32 v[64:65], v[140:141], v[188:189], v[64:65] op_sel_hi:[1,0,1] neg_lo:[1,0,0] neg_hi:[1,0,0]
	v_pk_fma_f32 v[66:67], v[112:113], v[188:189], v[66:67] op_sel_hi:[1,0,1]
	v_pk_fma_f32 v[142:143], v[202:203], v[218:219], v[136:137] op_sel_hi:[1,0,1]
	v_lshl_add_u64 v[80:81], s[8:9], 0, v[80:81]
	v_mul_f32_e32 v76, v76, v76
	v_mul_f32_e32 v72, v72, v72
	v_mul_f32_e32 v73, v73, v73
	v_mul_f32_e32 v74, v74, v74
	v_mul_f32_e32 v75, v75, v75
	v_pk_fma_f32 v[68:69], v[144:145], v[188:189], v[68:69] op_sel_hi:[1,0,1] neg_lo:[1,0,0] neg_hi:[1,0,0]
	v_pk_fma_f32 v[70:71], v[116:117], v[188:189], v[70:71] op_sel_hi:[1,0,1]
	v_pk_fma_f32 v[66:67], v[66:67], v[192:193], v[138:139] op_sel_hi:[1,0,1]
	v_pk_fma_f32 v[64:65], v[64:65], v[192:193], v[136:137] op_sel_hi:[1,0,1]
	v_max_f32_e32 v127, 0, v143
	v_lshl_add_u64 v[80:81], v[80:81], 0, v[190:191]
	v_cvt_pk_f16_f32 v72, v76, v72
	v_cvt_pk_f16_f32 v73, v73, v74
	v_cvt_pk_f16_f32 v74, v82, v77
	v_cvt_pk_f16_f32 v75, v78, v75
	v_pk_fma_f32 v[70:71], v[70:71], v[192:193], v[150:151] op_sel_hi:[1,0,1]
	v_pk_fma_f32 v[68:69], v[68:69], v[192:193], v[148:149] op_sel_hi:[1,0,1]
	v_max_f32_e32 v64, 0, v64
	v_max_f32_e32 v65, 0, v65
	v_max_f32_e32 v66, 0, v66
	v_mul_f32_e32 v127, v127, v127
	flat_store_dwordx4 v[80:81], v[72:75] sc1
	v_max_f32_e32 v68, 0, v68
	v_max_f32_e32 v67, 0, v67
	v_mul_f32_e32 v72, v64, v64
	v_max_f32_e32 v64, 0, v69
	v_mul_f32_e32 v69, v65, v65
	v_max_f32_e32 v65, 0, v70
	v_mul_f32_e32 v70, v66, v66
	v_max_f32_e32 v66, 0, v71
	v_pk_fma_f32 v[56:57], v[128:129], v[184:185], v[56:57] op_sel_hi:[1,0,1] neg_lo:[1,0,0] neg_hi:[1,0,0]
	v_mul_f32_e32 v68, v68, v68
	v_mul_f32_e32 v64, v64, v64
	v_mul_f32_e32 v65, v65, v65
	v_mul_f32_e32 v66, v66, v66
	v_mul_f32_e32 v67, v67, v67
	v_pk_fma_f32 v[60:61], v[132:133], v[184:185], v[60:61] op_sel_hi:[1,0,1] neg_lo:[1,0,0] neg_hi:[1,0,0]
	v_pk_fma_f32 v[58:59], v[178:179], v[184:185], v[58:59] op_sel_hi:[1,0,1]
	v_pk_fma_f32 v[56:57], v[56:57], v[126:127], v[152:153] op_sel_hi:[1,0,1]
	v_cvt_pk_f16_f32 v64, v68, v64
	v_cvt_pk_f16_f32 v65, v65, v66
	v_cvt_pk_f16_f32 v66, v72, v69
	v_cvt_pk_f16_f32 v67, v70, v67
	v_pk_fma_f32 v[62:63], v[134:135], v[184:185], v[62:63] op_sel_hi:[1,0,1]
	v_pk_fma_f32 v[60:61], v[60:61], v[126:127], v[156:157] op_sel_hi:[1,0,1]
	v_pk_fma_f32 v[58:59], v[58:59], v[126:127], v[154:155] op_sel_hi:[1,0,1]
	v_max_f32_e32 v56, 0, v56
	flat_store_dwordx4 v[80:81], v[64:67] offset:256 sc1
	v_pk_fma_f32 v[62:63], v[62:63], v[126:127], v[158:159] op_sel_hi:[1,0,1]
	v_max_f32_e32 v60, 0, v60
	v_mul_f32_e32 v66, v56, v56
	v_max_f32_e32 v56, 0, v61
	v_max_f32_e32 v57, 0, v57
	v_max_f32_e32 v58, 0, v58
	v_mul_f32_e32 v60, v60, v60
	v_mul_f32_e32 v56, v56, v56
	v_mul_f32_e32 v61, v57, v57
	v_max_f32_e32 v57, 0, v62
	v_mul_f32_e32 v62, v58, v58
	v_max_f32_e32 v58, 0, v63
	v_max_f32_e32 v59, 0, v59
	v_pk_fma_f32 v[48:49], v[140:141], v[184:185], v[48:49] op_sel_hi:[1,0,1] neg_lo:[1,0,0] neg_hi:[1,0,0]
	v_pk_fma_f32 v[50:51], v[112:113], v[184:185], v[50:51] op_sel_hi:[1,0,1]
	v_mul_f32_e32 v57, v57, v57
	v_mul_f32_e32 v58, v58, v58
	v_mul_f32_e32 v59, v59, v59
	v_cvt_pk_f16_f32 v56, v60, v56
	v_add_co_u32_e32 v60, vcc, s67, v176
	v_pk_fma_f32 v[52:53], v[144:145], v[184:185], v[52:53] op_sel_hi:[1,0,1] neg_lo:[1,0,0] neg_hi:[1,0,0]
	v_pk_fma_f32 v[54:55], v[116:117], v[184:185], v[54:55] op_sel_hi:[1,0,1]
	v_pk_fma_f32 v[50:51], v[50:51], v[126:127], v[138:139] op_sel_hi:[1,0,1]
	v_pk_fma_f32 v[48:49], v[48:49], v[126:127], v[136:137] op_sel_hi:[1,0,1]
	v_max_f32_e32 v125, 0, v147
	v_cvt_pk_f16_f32 v57, v57, v58
	v_cvt_pk_f16_f32 v58, v66, v61
	v_cvt_pk_f16_f32 v59, v62, v59
	v_addc_co_u32_e32 v61, vcc, 0, v177, vcc
	v_pk_fma_f32 v[54:55], v[54:55], v[126:127], v[150:151] op_sel_hi:[1,0,1]
	v_pk_fma_f32 v[52:53], v[52:53], v[126:127], v[148:149] op_sel_hi:[1,0,1]
	v_max_f32_e32 v48, 0, v48
	v_max_f32_e32 v49, 0, v49
	v_max_f32_e32 v50, 0, v50
	v_mul_f32_e32 v125, v125, v125
	flat_store_dwordx4 v[60:61], v[56:59] sc1
	v_max_f32_e32 v52, 0, v52
	v_max_f32_e32 v51, 0, v51
	v_mul_f32_e32 v56, v48, v48
	v_max_f32_e32 v48, 0, v53
	v_mul_f32_e32 v53, v49, v49
	v_max_f32_e32 v49, 0, v54
	v_mul_f32_e32 v54, v50, v50
;     __device__ __forceinline__ void operator()(const f32x4 (&acc)[2][2][4][2], const Unit& u, int wr, int wc, int fr, int fq) const {
;     ...
;                 for (int m = 0; m < 4; ++m) { const int row = row0 + ai * HALF + m * 16; bf16_t* rowp = O + (size_t)row * ldc + col0;
;                     const float mean = mean8[ai][m], rstd = rstd8[ai][m];
; #pragma unroll
;                     for (int bj = 0; bj < 2; ++bj) { f32x4 v0 = acc[ai][bj][m][0], v1 = acc[ai][bj][m][1];
;                         if (F == 1) { v0 = (v0 - c1v[bj][0] * mean) * rstd + c2v[bj][0]; v1 = (v1 - c1v[bj][1] * mean) * rstd + c2v[bj][1]; }
;                         if (kind == 1) {
; #pragma unroll
;                             for (int e = 0; e < 4; ++e) { float a = fmaxf(v0[e], 0.f), b_ = fmaxf(v1[e], 0.f); v0[e] = a * a; v1[e] = b_ * b_; } }
;                         u32x4 w; w.x = pk16(v0[0], v0[1]); w.y = pk16(v0[2], v0[3]); w.z = pk16(v1[0], v1[1]); w.w = pk16(v1[2], v1[3]);
;                         *(u32x4*)(rowp + bj * HALF) = w; } }
	v_max_f32_e32 v50, 0, v55
	v_pk_fma_f32 v[40:41], v[128:129], v[182:183], v[40:41] op_sel_hi:[1,0,1] neg_lo:[1,0,0] neg_hi:[1,0,0]
	v_mul_f32_e32 v52, v52, v52
	v_mul_f32_e32 v48, v48, v48
	v_mul_f32_e32 v49, v49, v49
	v_mul_f32_e32 v50, v50, v50
	v_mul_f32_e32 v51, v51, v51
	v_pk_fma_f32 v[44:45], v[132:133], v[182:183], v[44:45] op_sel_hi:[1,0,1] neg_lo:[1,0,0] neg_hi:[1,0,0]
	v_pk_fma_f32 v[42:43], v[178:179], v[182:183], v[42:43] op_sel_hi:[1,0,1]
	v_pk_fma_f32 v[40:41], v[40:41], v[124:125], v[152:153] op_sel_hi:[1,0,1]
	v_lshl_add_u64 v[64:65], v[176:177], 0, s[22:23]
	v_cvt_pk_f16_f32 v48, v52, v48
	v_cvt_pk_f16_f32 v49, v49, v50
	v_cvt_pk_f16_f32 v50, v56, v53
	v_cvt_pk_f16_f32 v51, v54, v51
	v_pk_fma_f32 v[46:47], v[134:135], v[182:183], v[46:47] op_sel_hi:[1,0,1]
	v_pk_fma_f32 v[44:45], v[44:45], v[124:125], v[156:157] op_sel_hi:[1,0,1]
	v_pk_fma_f32 v[42:43], v[42:43], v[124:125], v[154:155] op_sel_hi:[1,0,1]
	v_max_f32_e32 v40, 0, v40
	flat_store_dwordx4 v[64:65], v[48:51] offset:256 sc1
	v_pk_fma_f32 v[46:47], v[46:47], v[124:125], v[158:159] op_sel_hi:[1,0,1]
	v_max_f32_e32 v44, 0, v44
	v_mul_f32_e32 v50, v40, v40
	v_max_f32_e32 v40, 0, v45
	v_max_f32_e32 v41, 0, v41
	v_max_f32_e32 v42, 0, v42
	v_rsq_f32_e32 v122, v122
	v_mul_f32_e32 v44, v44, v44
	v_mul_f32_e32 v40, v40, v40
	v_mul_f32_e32 v45, v41, v41
	v_max_f32_e32 v41, 0, v46
	v_mul_f32_e32 v46, v42, v42
	v_max_f32_e32 v42, 0, v47
	v_max_f32_e32 v43, 0, v43
	v_pk_fma_f32 v[32:33], v[140:141], v[182:183], v[32:33] op_sel_hi:[1,0,1] neg_lo:[1,0,0] neg_hi:[1,0,0]
	v_pk_fma_f32 v[34:35], v[112:113], v[182:183], v[34:35] op_sel_hi:[1,0,1]
	v_mul_f32_e32 v41, v41, v41
	v_mul_f32_e32 v42, v42, v42
	v_mul_f32_e32 v43, v43, v43
	v_cvt_pk_f16_f32 v40, v44, v40
	v_add_co_u32_e32 v44, vcc, s68, v176
	v_pk_fma_f32 v[36:37], v[144:145], v[182:183], v[36:37] op_sel_hi:[1,0,1] neg_lo:[1,0,0] neg_hi:[1,0,0]
	v_pk_fma_f32 v[38:39], v[116:117], v[182:183], v[38:39] op_sel_hi:[1,0,1]
	v_pk_fma_f32 v[34:35], v[34:35], v[124:125], v[138:139] op_sel_hi:[1,0,1]
	v_pk_fma_f32 v[32:33], v[32:33], v[124:125], v[136:137] op_sel_hi:[1,0,1]
	v_max_f32_e32 v123, 0, v142
	v_cvt_pk_f16_f32 v41, v41, v42
	v_cvt_pk_f16_f32 v42, v50, v45
	v_cvt_pk_f16_f32 v43, v46, v43
	v_addc_co_u32_e32 v45, vcc, 0, v177, vcc
	v_pk_fma_f32 v[38:39], v[38:39], v[124:125], v[150:151] op_sel_hi:[1,0,1]
	v_pk_fma_f32 v[36:37], v[36:37], v[124:125], v[148:149] op_sel_hi:[1,0,1]
	v_max_f32_e32 v32, 0, v32
	v_max_f32_e32 v33, 0, v33
	v_max_f32_e32 v34, 0, v34
	v_mul_f32_e32 v123, v123, v123
	flat_store_dwordx4 v[44:45], v[40:43] sc1
	v_max_f32_e32 v36, 0, v36
	v_max_f32_e32 v35, 0, v35
	v_mul_f32_e32 v40, v32, v32
	v_max_f32_e32 v32, 0, v37
	v_mul_f32_e32 v37, v33, v33
	v_max_f32_e32 v33, 0, v38
	v_mul_f32_e32 v38, v34, v34
	v_max_f32_e32 v34, 0, v39
	v_pk_fma_f32 v[24:25], v[128:129], v[180:181], v[24:25] op_sel_hi:[1,0,1] neg_lo:[1,0,0] neg_hi:[1,0,0]
	v_mul_f32_e32 v36, v36, v36
	v_mul_f32_e32 v32, v32, v32
	v_mul_f32_e32 v33, v33, v33
	v_mul_f32_e32 v34, v34, v34
	v_mul_f32_e32 v35, v35, v35
	v_pk_fma_f32 v[28:29], v[132:133], v[180:181], v[28:29] op_sel_hi:[1,0,1] neg_lo:[1,0,0] neg_hi:[1,0,0]
	v_pk_fma_f32 v[26:27], v[178:179], v[180:181], v[26:27] op_sel_hi:[1,0,1]
	v_pk_fma_f32 v[24:25], v[24:25], v[122:123], v[152:153] op_sel_hi:[1,0,1]
	v_lshl_add_u64 v[48:49], v[176:177], 0, s[24:25]
	v_cvt_pk_f16_f32 v32, v36, v32
	v_cvt_pk_f16_f32 v33, v33, v34
	v_cvt_pk_f16_f32 v34, v40, v37
	v_cvt_pk_f16_f32 v35, v38, v35
	v_pk_fma_f32 v[30:31], v[134:135], v[180:181], v[30:31] op_sel_hi:[1,0,1]
	v_pk_fma_f32 v[28:29], v[28:29], v[122:123], v[156:157] op_sel_hi:[1,0,1]
	v_pk_fma_f32 v[26:27], v[26:27], v[122:123], v[154:155] op_sel_hi:[1,0,1]
	v_max_f32_e32 v24, 0, v24
	flat_store_dwordx4 v[48:49], v[32:35] offset:256 sc1
	v_pk_fma_f32 v[30:31], v[30:31], v[122:123], v[158:159] op_sel_hi:[1,0,1]
	v_max_f32_e32 v28, 0, v28
	v_mul_f32_e32 v34, v24, v24
	v_max_f32_e32 v24, 0, v29
	v_max_f32_e32 v25, 0, v25
	v_max_f32_e32 v26, 0, v26
	v_mul_f32_e32 v28, v28, v28
	v_mul_f32_e32 v24, v24, v24
	v_mul_f32_e32 v29, v25, v25
	v_max_f32_e32 v25, 0, v30
	v_mul_f32_e32 v30, v26, v26
	v_max_f32_e32 v26, 0, v31
	v_max_f32_e32 v27, 0, v27
	v_pk_fma_f32 v[16:17], v[140:141], v[180:181], v[16:17] op_sel_hi:[1,0,1] neg_lo:[1,0,0] neg_hi:[1,0,0]
	v_pk_fma_f32 v[18:19], v[112:113], v[180:181], v[18:19] op_sel_hi:[1,0,1]
	v_mul_f32_e32 v25, v25, v25
;     __device__ __forceinline__ void operator()(const f32x4 (&acc)[2][2][4][2], const Unit& u, int wr, int wc, int fr, int fq) const {
;     ...
;                 for (int m = 0; m < 4; ++m) { const int row = row0 + ai * HALF + m * 16; bf16_t* rowp = O + (size_t)row * ldc + col0;
;                     const float mean = mean8[ai][m], rstd = rstd8[ai][m];
; #pragma unroll
;                     for (int bj = 0; bj < 2; ++bj) { f32x4 v0 = acc[ai][bj][m][0], v1 = acc[ai][bj][m][1];
;                         if (F == 1) { v0 = (v0 - c1v[bj][0] * mean) * rstd + c2v[bj][0]; v1 = (v1 - c1v[bj][1] * mean) * rstd + c2v[bj][1]; }
;                         if (kind == 1) {
; #pragma unroll
;                             for (int e = 0; e < 4; ++e) { float a = fmaxf(v0[e], 0.f), b_ = fmaxf(v1[e], 0.f); v0[e] = a * a; v1[e] = b_ * b_; } }
;                         u32x4 w; w.x = pk16(v0[0], v0[1]); w.y = pk16(v0[2], v0[3]); w.z = pk16(v1[0], v1[1]); w.w = pk16(v1[2], v1[3]);
;                         *(u32x4*)(rowp + bj * HALF) = w; } }
	v_mul_f32_e32 v26, v26, v26
	v_mul_f32_e32 v27, v27, v27
	v_cvt_pk_f16_f32 v24, v28, v24
	v_add_co_u32_e32 v28, vcc, s69, v176
	v_pk_fma_f32 v[20:21], v[144:145], v[180:181], v[20:21] op_sel_hi:[1,0,1] neg_lo:[1,0,0] neg_hi:[1,0,0]
	v_pk_fma_f32 v[22:23], v[116:117], v[180:181], v[22:23] op_sel_hi:[1,0,1]
	v_pk_fma_f32 v[18:19], v[18:19], v[122:123], v[138:139] op_sel_hi:[1,0,1]
	v_pk_fma_f32 v[16:17], v[16:17], v[122:123], v[136:137] op_sel_hi:[1,0,1]
	v_max_f32_e32 v121, 0, v146
	v_cvt_pk_f16_f32 v25, v25, v26
	v_cvt_pk_f16_f32 v26, v34, v29
	v_cvt_pk_f16_f32 v27, v30, v27
	v_addc_co_u32_e32 v29, vcc, 0, v177, vcc
	v_pk_fma_f32 v[22:23], v[22:23], v[122:123], v[150:151] op_sel_hi:[1,0,1]
	v_pk_fma_f32 v[20:21], v[20:21], v[122:123], v[148:149] op_sel_hi:[1,0,1]
	v_max_f32_e32 v16, 0, v16
	v_max_f32_e32 v17, 0, v17
	v_max_f32_e32 v18, 0, v18
	v_mul_f32_e32 v121, v121, v121
	flat_store_dwordx4 v[28:29], v[24:27] sc1
	v_max_f32_e32 v20, 0, v20
	v_max_f32_e32 v19, 0, v19
	v_mul_f32_e32 v24, v16, v16
	v_max_f32_e32 v16, 0, v21
	v_mul_f32_e32 v21, v17, v17
	v_max_f32_e32 v17, 0, v22
	v_mul_f32_e32 v22, v18, v18
	v_max_f32_e32 v18, 0, v23
	v_pk_fma_f32 v[8:9], v[128:129], v[130:131], v[8:9] op_sel_hi:[1,0,1] neg_lo:[1,0,0] neg_hi:[1,0,0]
	v_mul_f32_e32 v20, v20, v20
	v_mul_f32_e32 v16, v16, v16
	v_mul_f32_e32 v17, v17, v17
	v_mul_f32_e32 v18, v18, v18
	v_mul_f32_e32 v19, v19, v19
	v_pk_fma_f32 v[12:13], v[132:133], v[130:131], v[12:13] op_sel_hi:[1,0,1] neg_lo:[1,0,0] neg_hi:[1,0,0]
	v_pk_fma_f32 v[10:11], v[178:179], v[130:131], v[10:11] op_sel_hi:[1,0,1]
	v_pk_fma_f32 v[8:9], v[8:9], v[120:121], v[152:153] op_sel_hi:[1,0,1]
	v_lshl_add_u64 v[32:33], v[176:177], 0, s[26:27]
	v_cvt_pk_f16_f32 v16, v20, v16
	v_cvt_pk_f16_f32 v17, v17, v18
	v_cvt_pk_f16_f32 v18, v24, v21
	v_cvt_pk_f16_f32 v19, v22, v19
	v_pk_fma_f32 v[14:15], v[134:135], v[130:131], v[14:15] op_sel_hi:[1,0,1]
	v_pk_fma_f32 v[12:13], v[12:13], v[120:121], v[156:157] op_sel_hi:[1,0,1]
	v_pk_fma_f32 v[10:11], v[10:11], v[120:121], v[154:155] op_sel_hi:[1,0,1]
	v_max_f32_e32 v8, 0, v8
	flat_store_dwordx4 v[32:33], v[16:19] offset:256 sc1
	v_pk_fma_f32 v[14:15], v[14:15], v[120:121], v[158:159] op_sel_hi:[1,0,1]
	v_max_f32_e32 v12, 0, v12
	v_mul_f32_e32 v18, v8, v8
	v_max_f32_e32 v8, 0, v13
	v_max_f32_e32 v9, 0, v9
	v_max_f32_e32 v10, 0, v10
	v_mul_f32_e32 v12, v12, v12
	v_mul_f32_e32 v8, v8, v8
	v_mul_f32_e32 v13, v9, v9
	v_max_f32_e32 v9, 0, v14
	v_mul_f32_e32 v14, v10, v10
	v_max_f32_e32 v10, 0, v15
	v_max_f32_e32 v11, 0, v11
	v_pk_fma_f32 v[0:1], v[140:141], v[130:131], v[0:1] op_sel_hi:[1,0,1] neg_lo:[1,0,0] neg_hi:[1,0,0]
	v_pk_fma_f32 v[2:3], v[112:113], v[130:131], v[2:3] op_sel_hi:[1,0,1]
	v_mul_f32_e32 v9, v9, v9
	v_mul_f32_e32 v10, v10, v10
	v_mul_f32_e32 v11, v11, v11
	v_cvt_pk_f16_f32 v8, v12, v8
	v_add_co_u32_e32 v12, vcc, s70, v176
	v_pk_fma_f32 v[4:5], v[144:145], v[130:131], v[4:5] op_sel_hi:[1,0,1] neg_lo:[1,0,0] neg_hi:[1,0,0]
	v_pk_fma_f32 v[6:7], v[116:117], v[130:131], v[6:7] op_sel_hi:[1,0,1]
	v_pk_fma_f32 v[2:3], v[2:3], v[120:121], v[138:139] op_sel_hi:[1,0,1]
	v_pk_fma_f32 v[0:1], v[0:1], v[120:121], v[136:137] op_sel_hi:[1,0,1]
	v_cvt_pk_f16_f32 v9, v9, v10
	v_cvt_pk_f16_f32 v10, v18, v13
	v_cvt_pk_f16_f32 v11, v14, v11
	v_addc_co_u32_e32 v13, vcc, 0, v177, vcc
	v_pk_fma_f32 v[6:7], v[6:7], v[120:121], v[150:151] op_sel_hi:[1,0,1]
	v_pk_fma_f32 v[4:5], v[4:5], v[120:121], v[148:149] op_sel_hi:[1,0,1]
	v_max_f32_e32 v0, 0, v0
	v_max_f32_e32 v1, 0, v1
	v_max_f32_e32 v2, 0, v2
	flat_store_dwordx4 v[12:13], v[8:11] sc1
	v_max_f32_e32 v4, 0, v4
	v_max_f32_e32 v3, 0, v3
	v_mul_f32_e32 v8, v0, v0
	v_max_f32_e32 v0, 0, v5
	v_mul_f32_e32 v5, v1, v1
	v_max_f32_e32 v1, 0, v6
	v_mul_f32_e32 v6, v2, v2
	v_max_f32_e32 v2, 0, v7
	v_mul_f32_e32 v4, v4, v4
	v_mul_f32_e32 v0, v0, v0
	v_mul_f32_e32 v1, v1, v1
	v_mul_f32_e32 v2, v2, v2
	v_mul_f32_e32 v3, v3, v3
	v_cvt_pk_f16_f32 v208, v121, v125
	v_cvt_pk_f16_f32 v210, v123, v127
	v_lshl_add_u64 v[16:17], v[176:177], 0, s[28:29]
	v_cvt_pk_f16_f32 v0, v4, v0
	v_cvt_pk_f16_f32 v1, v1, v2
	v_cvt_pk_f16_f32 v2, v8, v5
	v_cvt_pk_f16_f32 v3, v6, v3
	s_andn2_b64 vcc, exec, s[6:7]
	s_mov_b64 s[6:7], -1
	flat_store_dwordx4 v[176:177], v[208:211] offset:256 sc1
	flat_store_dwordx4 v[16:17], v[0:3] offset:256 sc1
	s_cbranch_vccnz .LBB0_1159
	s_andn2_b64 vcc, exec, s[0:1]
	s_cbranch_vccnz .LBB0_1158
	s_barrier
	s_branch .LBB0_1158
